# per-unit re-sync of the two wave groups in swiglu+proj GEMMs: both groups run the epilogue concurrently (extra barrier after K-loop for wr0, before K-loop for wr1)
# speedup vs baseline: 1.0301x; 1.0102x over previous
; __device__ __forceinline__ int otid() { int t = threadIdx.x; asm volatile("" : "+v"(t)); return t; }
; #define PG8_STAGE(bufoff, gbase, voff) do { _Pragma("unroll") for (int _i = 0; _i < 2; ++_i) \
;         __builtin_amdgcn_global_load_lds((const unsigned*)((const char*)(gbase) + (voff)[_i]), (LAS unsigned*)(lds + (bufoff) + ldsw + _i * 8192), 16, 0, 0); } while (0)
; #define PG8_WAIT_V(n) asm volatile("s_waitcnt vmcnt(" #n ")" ::: "memory")
; #define PG8_BAR __builtin_amdgcn_s_barrier()
; template <class Epi>
; __device__ __forceinline__ void gemm_phase(LAS unsigned char* lds, const Gemm g, const Sched& S, const Epi& E) {
;     const int tid = otid(), wid = __builtin_amdgcn_readfirstlane(tid >> 6), lane = tid & 63, wr = wid >> 2, wc = wid & 3, fr = lane & 15, fq = lane >> 4;
;     const int nt = g.K / BK;
;     unsigned voffA[2], voffB[2];
; #pragma unroll
;     for (int i = 0; i < 2; ++i) { int R, C; stage_rc(tid * 16 + i * 8192, R, C); const int Rb = Epi::PERM ? ((R & ~31) + perm32(R & 31)) : R;
;         voffA[i] = (unsigned)(R * g.lda + C) * 2u; voffB[i] = (unsigned)(Rb * g.ldb + C) * 2u; }
;     const size_t kstep = (size_t)(BK * 2);
;     const size_t hstepA = (size_t)HALF * g.lda * 2, hstepB = (size_t)HALF * g.ldb * 2;
;     const unsigned ldsw = (unsigned)wid * 1024u;
;     const int aoff = lds_byte(wr * 64 + fr, fq * 8), boff = lds_byte(wc * 32 + fr, fq * 8);
;     ...
;     Unit cur, nxt; int ui = 0;
;     if (!S.next(0, cur)) return;
;     f32x4 acc[2][2][4][2];
; #pragma unroll
;     for (int a = 0; a < 2; ++a)
; #pragma unroll
;         for (int b = 0; b < 2; ++b)
; #pragma unroll
;             for (int m = 0; m < 4; ++m)
; #pragma unroll
;                 for (int n = 0; n < 2; ++n) acc[a][b][m][n] = (f32x4){0.f, 0.f, 0.f, 0.f};
;     bf16x8 At[4][2], B0[2][2], B1[2][2];
;     const char* cA = (const char*)g.A + cur.ao; const char* cB = (const char*)g.Bt + cur.bo;
;     PG8_STAGE(PG8_SB(0, 0), cB, voffB); PG8_STAGE(PG8_SA(0, 0), cA, voffA); PG8_STAGE(PG8_SB(0, 1), cB + hstepB, voffB); PG8_STAGE(PG8_SA(0, 1), cA + hstepA, voffA);
;     if (wr == 1) PG8_BAR;
;     PG8_WAIT_V(4); PG8_BAR;
;     PG8_STAGE(PG8_SB(1, 0), cB + kstep, voffB); PG8_STAGE(PG8_SA(1, 0), cA + kstep, voffA); PG8_STAGE(PG8_SB(1, 1), cB + hstepB + kstep, voffB);
;     PG8_WAIT_V(6); PG8_BAR;
.LBB0_632:
	s_andn2_b64 vcc, exec, s[0:1]
	s_cbranch_vccnz .LBB0_694
	s_waitcnt vmcnt(0)
	v_bfe_i32 v4, v0, 27, 1
	v_lshlrev_b32_e32 v2, 4, v0
	v_lshrrev_b32_e32 v4, 22, v4
	v_add_u32_e32 v4, v2, v4
	v_and_b32_e32 v4, 0xfffffc00, v4
	v_ashrrev_i32_e32 v3, 31, v0
	v_sub_u32_e32 v4, v2, v4
	v_lshrrev_b32_e32 v3, 26, v3
	v_lshrrev_b32_e32 v5, 4, v4
	v_add_u32_e32 v3, v0, v3
	v_bitop3_b32 v5, v5, v4, 32 bitop3:0x6c
	v_ashrrev_i32_e32 v4, 31, v4
	v_ashrrev_i32_e32 v3, 6, v3
	v_lshrrev_b32_e32 v4, 26, v4
	v_lshlrev_b32_e32 v6, 3, v3
	v_add_u32_e32 v4, v5, v4
	v_and_b32_e32 v6, -16, v6
	v_ashrrev_i32_e32 v4, 6, v4
	v_lshlrev_b32_e32 v3, 5, v3
	v_add_u32_e32 v6, v4, v6
	v_and_b32_e32 v14, 32, v3
	v_mul_i32_i24_e32 v3, 64, v4
	v_sub_u32_e32 v3, v5, v3
	v_mov_b32_e32 v8, 1
	v_lshlrev_b32_e32 v5, 1, v6
	v_lshrrev_b32_e32 v7, 2, v6
	v_and_b32_e32 v4, 3, v4
	s_mov_b32 s0, 0x7fffffe0
	v_ashrrev_i16_sdwa v3, v8, sext(v3) dst_sel:DWORD dst_unused:UNUSED_PAD src0_sel:DWORD src1_sel:BYTE_0
	v_and_b32_e32 v5, 24, v5
	v_and_b32_e32 v7, 4, v7
	v_and_or_b32 v4, v6, s0, v4
	v_bfe_i32 v15, v3, 0, 16
	v_or3_b32 v4, v4, v7, v5
	v_add_u32_e32 v3, v14, v15
	v_mul_lo_u32 v16, v6, s82
	v_mul_lo_u32 v4, v4, s66
	v_add_u32_e32 v2, 0x2000, v2
	v_add_lshl_u32 v178, v3, v16, 1
	v_add_lshl_u32 v180, v4, v3, 1
	v_ashrrev_i32_e32 v3, 31, v2
	v_lshrrev_b32_e32 v3, 22, v3
	v_add_u32_e32 v3, v2, v3
	v_ashrrev_i32_e32 v3, 10, v3
	v_mul_i32_i24_e32 v4, 0x400, v3
	v_sub_u32_e32 v2, v2, v4
	v_lshrrev_b32_e32 v4, 4, v2
	v_bitop3_b32 v2, v4, v2, 32 bitop3:0x6c
	v_ashrrev_i32_e32 v5, 31, v2
	v_lshrrev_b32_e32 v5, 26, v5
	v_writelane_b32 v254, s57, 37
	v_lshlrev_b32_e32 v4, 3, v3
	v_add_u32_e32 v5, v2, v5
	v_writelane_b32 v254, s90, 39
	v_and_b32_e32 v4, -16, v4
	v_ashrrev_i32_e32 v6, 6, v5
	v_lshlrev_b32_e32 v3, 5, v3
	v_writelane_b32 v254, s91, 40
	v_add_u32_e32 v4, v6, v4
	v_and_b32_e32 v17, 32, v3
	v_and_b32_e32 v3, 0xc0, v5
	v_sub_u32_e32 v2, v2, v3
	v_lshlrev_b32_e32 v3, 1, v4
	v_lshrrev_b32_e32 v5, 2, v4
	v_and_b32_e32 v6, 3, v6
	v_writelane_b32 v254, s35, 29
	v_and_b32_e32 v3, 24, v3
	v_and_b32_e32 v5, 4, v5
	v_and_or_b32 v6, v4, s0, v6
	v_mul_lo_u32 v19, v4, s82
	v_writelane_b32 v254, s82, 43
	v_or3_b32 v3, v6, v5, v3
	s_ashr_i32 s2, s35, 6
	v_writelane_b32 v254, s83, 44
	s_ashr_i32 s14, s35, 8
	v_mul_lo_u32 v3, v3, s66
	s_lshl_b64 s[6:7], s[82:83], 8
	v_writelane_b32 v254, s66, 45
	s_lshl_b64 s[36:37], s[66:67], 8
	s_lshl_b32 s88, s2, 10
	s_add_u32 s4, s10, s4
	v_ashrrev_i16_sdwa v2, v8, sext(v2) dst_sel:DWORD dst_unused:UNUSED_PAD src0_sel:DWORD src1_sel:BYTE_0
	s_addc_u32 s5, s11, s5
	s_add_i32 s89, s88, 0
	v_bfe_i32 v18, v2, 0, 16
	v_writelane_b32 v254, s67, 46
	s_add_i32 m0, s89, 0x10000
	v_add_u32_e32 v2, v17, v18
	global_load_lds_dwordx4 v180, s[4:5]
	s_add_i32 m0, s89, 0x12000
	v_readlane_b32 s0, v254, 11
	v_add_lshl_u32 v184, v3, v2, 1
	v_readlane_b32 s1, v254, 12
	s_add_u32 s0, s0, s40
	global_load_lds_dwordx4 v184, s[4:5]
	s_addc_u32 s1, s1, s41
	s_mov_b32 m0, s89
	s_add_i32 s90, s89, 0x2000
	v_add_lshl_u32 v182, v2, v19, 1
	global_load_lds_dwordx4 v178, s[0:1]
	s_mov_b32 m0, s90
	s_add_u32 s34, s4, s36
	global_load_lds_dwordx4 v182, s[0:1]
	s_addc_u32 s35, s5, s37
	s_add_i32 m0, s89, 0x14000
	v_mov_b32_e32 v181, v1
	v_mov_b32_e32 v185, v1
	global_load_lds_dwordx4 v180, s[34:35]
	s_add_i32 m0, s89, 0x16000
	v_lshl_add_u64 v[10:11], s[34:35], 0, v[180:181]
	v_lshl_add_u64 v[12:13], s[34:35], 0, v[184:185]
	global_load_lds_dwordx4 v184, s[34:35]
	s_add_u32 s34, s0, s6
	s_addc_u32 s35, s1, s7
	s_add_i32 s91, s89, 0x4000
	s_mov_b32 m0, s91
	s_add_i32 s92, s89, 0x6000
	global_load_lds_dwordx4 v178, s[34:35]
	s_mov_b32 m0, s92
	v_mov_b32_e32 v179, v1
	global_load_lds_dwordx4 v182, s[34:35]
	v_mov_b32_e32 v183, v1
	v_lshl_add_u64 v[2:3], s[4:5], 0, v[180:181]
	v_lshl_add_u64 v[4:5], s[4:5], 0, v[184:185]
	v_lshl_add_u64 v[6:7], s[0:1], 0, v[178:179]
	v_lshl_add_u64 v[8:9], s[0:1], 0, v[182:183]
	s_cmp_lg_u32 s14, 1
	s_cbranch_scc1 .LBB0_635
.LBB0_635:
	s_add_i32 m0, s89, 0x18000
	v_lshl_add_u64 v[2:3], v[2:3], 0, s[60:61]
	s_waitcnt vmcnt(0)
	s_barrier
	global_load_lds_dwordx4 v[2:3], off
	v_lshl_add_u64 v[2:3], v[4:5], 0, s[60:61]
	s_add_i32 m0, s89, 0x1a000
	s_add_i32 s93, s89, 0x8000
	global_load_lds_dwordx4 v[2:3], off
	v_lshl_add_u64 v[2:3], v[6:7], 0, s[60:61]
	s_mov_b32 m0, s93
	s_add_i32 s94, s89, 0xa000
	global_load_lds_dwordx4 v[2:3], off
	v_lshl_add_u64 v[2:3], v[8:9], 0, s[60:61]
	s_mov_b32 m0, s94
	v_lshrrev_b32_e32 v20, 1, v0
	global_load_lds_dwordx4 v[2:3], off
	s_add_i32 m0, s89, 0x1c000
	v_lshl_add_u64 v[2:3], v[10:11], 0, s[60:61]
	global_load_lds_dwordx4 v[2:3], off
	v_lshl_add_u64 v[2:3], v[12:13], 0, s[60:61]
	s_add_i32 m0, s89, 0x1e000
	v_and_b32_e32 v20, 24, v20
	global_load_lds_dwordx4 v[2:3], off
	v_and_b32_e32 v234, 15, v0
	v_lshlrev_b32_e32 v21, 1, v20
	v_lshlrev_b32_e32 v0, 2, v0
	s_and_b32 s8, s2, 3
	s_lshl_b32 s9, s14, 6
	v_lshl_or_b32 v21, v234, 6, v21
	s_lshl_b32 s14, s14, 13
	v_and_b32_e32 v0, 32, v0
	v_bitop3_b32 v22, v21, s14, v0 bitop3:0xde
	s_lshl_b32 s14, s8, 5
	s_lshl_b32 s8, s8, 12
	v_bitop3_b32 v236, v21, s8, v0 bitop3:0xde
	v_and_b32_e32 v0, 63, v219
	v_or_b32_e32 v235, s9, v234
	v_or_b32_e32 v237, s9, v0
	s_lshl_b32 s2, s2, 6
	v_readlane_b32 s8, v253, 61
	s_add_i32 s95, s73, -2
	s_and_b32 s2, s2, 0x80
	v_readlane_b32 s9, v253, 62
	s_cmp_eq_u64 s[8:9], 0
	s_cselect_b64 s[76:77], -1, 0
	s_cmp_lg_u64 s[8:9], 0
	v_readlane_b32 s8, v254, 13
	s_cselect_b64 s[78:79], -1, 0
	s_ashr_i32 s96, s8, 31
	s_lshr_b32 s8, s54, 3
	v_and_or_b32 v2, s14, 32, v20
	v_writelane_b32 v253, s8, 30
	s_add_i32 s65, s8, 1
	v_readlane_b32 s8, v254, 5
	v_readlane_b32 s9, v254, 37
	s_mul_i32 s97, s8, s9
	v_lshlrev_b32_e32 v0, 3, v2
	v_lshl_add_u64 v[186:187], s[84:85], 0, v[0:1]
	v_cvt_f32_u32_e32 v0, s97
	s_sub_i32 s8, 0, s97
	s_waitcnt vmcnt(6)
	v_or_b32_e32 v238, s14, v20
	v_rcp_iflag_f32_e32 v0, v0
	s_mov_b32 s27, s39
	s_and_b32 s71, s54, 7
	s_mov_b32 s67, s39
	v_mul_f32_e32 v0, 0x4f7ffffe, v0
	v_cvt_u32_f32_e32 v0, v0
	s_mov_b32 s42, 0
	v_add_u32_e32 v239, 0, v22
	s_lshl_b32 s66, s2, 1
	v_readfirstlane_b32 s9, v0
	v_cvt_f32_u32_e32 v0, s25
	s_mul_i32 s8, s8, s9
	s_mul_hi_u32 s8, s9, s8
	s_add_i32 s43, s9, s8
	v_rcp_iflag_f32_e32 v0, v0
	s_sub_i32 s8, 0, s25
	s_barrier
	v_mul_f32_e32 v0, 0x4f7ffffe, v0
	v_cvt_u32_f32_e32 v0, v0
	s_nop 0
	v_readfirstlane_b32 s9, v0
	v_add_u32_e32 v0, v16, v14
	v_add_lshl_u32 v0, v0, v15, 1
	s_mul_i32 s8, s8, s9
	v_lshl_add_u64 v[188:189], s[6:7], 0, v[0:1]
	v_add_u32_e32 v0, v19, v17
	s_mul_hi_u32 s8, s9, s8
	v_add_lshl_u32 v0, v0, v18, 1
	s_add_i32 s52, s9, s8
	v_lshl_add_u64 v[190:191], s[6:7], 0, v[0:1]
	v_lshlrev_b32_e32 v0, 1, v2
	s_branch .LBB0_637

; #define PG8_STAGE(bufoff, gbase, voff) do { _Pragma("unroll") for (int _i = 0; _i < 2; ++_i) \
;         __builtin_amdgcn_global_load_lds((const unsigned*)((const char*)(gbase) + (voff)[_i]), (LAS unsigned*)(lds + (bufoff) + ldsw + _i * 8192), 16, 0, 0); } while (0)
; #define PG8_LDA(dst, b, h) do { _Pragma("unroll") for (int m = 0; m < 4; ++m) _Pragma("unroll") for (int k = 0; k < 2; ++k) dst[m][k] = *(const LAS bf16x8*)(lds + PG8_SA(b, h) + aoff + m * 2048 + k * 1024); } while (0)
; #define PG8_LDB(dst, b, h) do { _Pragma("unroll") for (int n = 0; n < 2; ++n) _Pragma("unroll") for (int k = 0; k < 2; ++k) dst[n][k] = *(const LAS bf16x8*)(lds + PG8_SB(b, h) + boff + n * 2048 + k * 1024); } while (0)
; #define PG8_MMA(ai, bj, At, Bt) do { __builtin_amdgcn_s_setprio(1); _Pragma("unroll") for (int m = 0; m < 4; ++m) _Pragma("unroll") for (int n = 0; n < 2; ++n) _Pragma("unroll") for (int k = 0; k < 2; ++k) \
;         acc[ai][bj][m][n] = __builtin_amdgcn_mfma_f32_16x16x32_bf16(Bt[n][k], At[m][k], acc[ai][bj][m][n], 0, 0, 0); __builtin_amdgcn_s_setprio(0); } while (0)
; #define PG8_WAIT_L(n) asm volatile("s_waitcnt lgkmcnt(" #n ")" ::: "memory")
; #define PG8_BAR __builtin_amdgcn_s_barrier()
; #define PG8_SCHED __builtin_amdgcn_sched_barrier(0)
; template <class Epi>
; __device__ __forceinline__ void gemm_phase(LAS unsigned char* lds, const Gemm g, const Sched& S, const Epi& E) {
;     ...
;         for (int t = 0; t < nt; t += 2) {
;             const bool last = (t == nt - 2);
;             const char* a1 = cA + (size_t)(t + 1) * kstep;
;             const char* a2 = last ? nA : cA + (size_t)(t + 2) * kstep; const char* b2 = last ? nB : cB + (size_t)(t + 2) * kstep;
;             const char* a3 = a2 + kstep; const char* b3 = b2 + kstep;
;             PG8_LDB(B0, 0, 0); PG8_SCHED; PG8_LDA(At, 0, 0); PG8_STAGE(PG8_SA(1, 1), a1 + hstepA, voffA);
;             PG8_WAIT_L(8); PG8_BAR; PG8_WAIT_L(0); PG8_MMA(0, 0, At, B0); PG8_BAR; PG8_SCHED;
;     ...
; #pragma unroll
;         for (int a = 0; a < 2; ++a)
; #pragma unroll
;             for (int b = 0; b < 2; ++b)
; #pragma unroll
;                 for (int m = 0; m < 4; ++m)
; #pragma unroll
;                     for (int n = 0; n < 2; ++n) acc[a][b][m][n] = (f32x4){0.f, 0.f, 0.f, 0.f};
;         cur = nxt; cA = nA; cB = nB; ++ui;
.LBB0_648:
	v_mov_b64_e32 v[2:3], s[26:27]
	v_readlane_b32 s8, v254, 11
	v_cmp_lt_i64_e32 vcc, s[82:83], v[2:3]
	v_readlane_b32 s9, v254, 12
	s_add_u32 s82, s8, s38
	s_addc_u32 s83, s9, s39
	s_and_b64 s[14:15], vcc, exec
	s_cselect_b32 s33, s83, s1
	s_cselect_b32 s48, s82, s0
	s_add_u32 s84, s10, s80
	s_addc_u32 s85, s11, s81
	s_and_b64 s[14:15], vcc, exec
	s_cselect_b32 s51, s85, s5
	s_cselect_b32 s55, s84, s4
	s_add_u32 s0, s0, 0x80
	s_addc_u32 s1, s1, 0
	s_add_u32 s34, s4, 0x100
	v_mov_b32_e32 v2, 0
	s_addc_u32 s35, s5, 0
	s_mov_b32 s4, 0
	v_mov_b32_e32 v3, v2
	v_mov_b32_e32 v4, v2
	v_mov_b32_e32 v5, v2
	v_mov_b32_e32 v6, v2
	v_mov_b32_e32 v7, v2
	v_mov_b32_e32 v8, v2
	v_mov_b32_e32 v9, v2
	v_mov_b32_e32 v18, v2
	v_mov_b32_e32 v19, v2
	v_mov_b32_e32 v20, v2
	v_mov_b32_e32 v21, v2
	v_mov_b32_e32 v22, v2
	v_mov_b32_e32 v23, v2
	v_mov_b32_e32 v24, v2
	v_mov_b32_e32 v25, v2
	v_mov_b32_e32 v34, v2
	v_mov_b32_e32 v35, v2
	v_mov_b32_e32 v36, v2
	v_mov_b32_e32 v37, v2
	v_mov_b32_e32 v38, v2
	v_mov_b32_e32 v39, v2
	v_mov_b32_e32 v40, v2
	v_mov_b32_e32 v41, v2
	v_mov_b32_e32 v50, v2
	v_mov_b32_e32 v51, v2
	v_mov_b32_e32 v52, v2
	v_mov_b32_e32 v53, v2
	v_mov_b32_e32 v54, v2
	v_mov_b32_e32 v55, v2
	v_mov_b32_e32 v56, v2
	v_mov_b32_e32 v57, v2
	v_mov_b32_e32 v10, v2
	v_mov_b32_e32 v11, v2
	v_mov_b32_e32 v12, v2
	v_mov_b32_e32 v13, v2
	v_mov_b32_e32 v14, v2
	v_mov_b32_e32 v15, v2
	v_mov_b32_e32 v16, v2
	v_mov_b32_e32 v17, v2
	v_mov_b32_e32 v26, v2
	v_mov_b32_e32 v27, v2
	v_mov_b32_e32 v28, v2
	v_mov_b32_e32 v29, v2
	v_mov_b32_e32 v30, v2
	v_mov_b32_e32 v31, v2
	v_mov_b32_e32 v32, v2
	v_mov_b32_e32 v33, v2
	v_mov_b32_e32 v42, v2
	v_mov_b32_e32 v43, v2
	v_mov_b32_e32 v44, v2
	v_mov_b32_e32 v45, v2
	v_mov_b32_e32 v46, v2
	s_waitcnt lgkmcnt(0)
	v_mov_b32_e32 v47, v2
	v_mov_b32_e32 v48, v2
	v_mov_b32_e32 v49, v2
	v_mov_b32_e32 v58, v2
	v_mov_b32_e32 v59, v2
	v_mov_b32_e32 v60, v2
	v_mov_b32_e32 v61, v2
	v_mov_b32_e32 v62, v2
	v_mov_b32_e32 v63, v2
	v_mov_b32_e32 v64, v2
	v_mov_b32_e32 v65, v2
	v_mov_b32_e32 v66, v2
	v_mov_b32_e32 v67, v2
	v_mov_b32_e32 v68, v2
	v_mov_b32_e32 v69, v2
	v_mov_b32_e32 v70, v2
	v_mov_b32_e32 v71, v2
	v_mov_b32_e32 v72, v2
	v_mov_b32_e32 v73, v2
	v_mov_b32_e32 v82, v2
	v_mov_b32_e32 v83, v2
	v_mov_b32_e32 v84, v2
	v_mov_b32_e32 v85, v2
	v_mov_b32_e32 v86, v2
	v_mov_b32_e32 v87, v2
	v_mov_b32_e32 v88, v2
	v_mov_b32_e32 v89, v2
	v_mov_b32_e32 v98, v2
	v_mov_b32_e32 v99, v2
	v_mov_b32_e32 v100, v2
	v_mov_b32_e32 v101, v2
	v_mov_b32_e32 v102, v2
	v_mov_b32_e32 v103, v2
	v_mov_b32_e32 v104, v2
	v_mov_b32_e32 v105, v2
	v_mov_b32_e32 v114, v2
	v_mov_b32_e32 v115, v2
	v_mov_b32_e32 v116, v2
	v_mov_b32_e32 v117, v2
	v_mov_b32_e32 v118, v2
	v_mov_b32_e32 v119, v2
	v_mov_b32_e32 v120, v2
	v_mov_b32_e32 v121, v2
	v_mov_b32_e32 v74, v2
	v_mov_b32_e32 v75, v2
	v_mov_b32_e32 v76, v2
	v_mov_b32_e32 v77, v2
	v_mov_b32_e32 v78, v2
	v_mov_b32_e32 v79, v2
	v_mov_b32_e32 v80, v2
	v_mov_b32_e32 v81, v2
	v_mov_b32_e32 v90, v2
	v_mov_b32_e32 v91, v2
	v_mov_b32_e32 v92, v2
	v_mov_b32_e32 v93, v2
	v_mov_b32_e32 v94, v2
	v_mov_b32_e32 v95, v2
	v_mov_b32_e32 v96, v2
	v_mov_b32_e32 v97, v2
	v_mov_b32_e32 v106, v2
	v_mov_b32_e32 v107, v2
	v_mov_b32_e32 v108, v2
	v_mov_b32_e32 v109, v2
	v_mov_b32_e32 v110, v2
	v_mov_b32_e32 v111, v2
	v_mov_b32_e32 v112, v2
	v_mov_b32_e32 v113, v2
	v_mov_b32_e32 v122, v2
	v_mov_b32_e32 v123, v2
	v_mov_b32_e32 v124, v2
	v_mov_b32_e32 v125, v2
	v_mov_b32_e32 v126, v2
	v_mov_b32_e32 v127, v2
	v_mov_b32_e32 v128, v2
	v_mov_b32_e32 v129, v2
	v_readfirstlane_b32 s98, v219
	s_nop 1
	s_bitcmp1_b32 s98, 8
	s_cbranch_scc0 .Lresync_y_649
	s_barrier
.Lresync_y_649:
.LBB0_649:
	s_add_i32 s14, s4, 2
	s_add_u32 s8, s0, 0x80
	s_addc_u32 s5, s1, 0
	s_add_i32 s9, 0, 0x10000
	v_add_u32_e32 v144, s9, v236
	ds_read_b128 v[132:135], v144
	ds_read_b128 v[136:139], v144 offset:1024
	ds_read_b128 v[140:143], v144 offset:2048
	ds_read_b128 v[144:147], v144 offset:3072
	s_cmp_eq_u32 s95, s4
	s_cselect_b32 s4, s48, s8
	s_cselect_b32 s5, s33, s5
	s_cselect_b32 s87, s51, s35
	s_cselect_b32 s86, s55, s34
	v_lshl_add_u64 v[176:177], s[0:1], 0, v[188:189]
	s_add_i32 m0, s89, 0xc000
	ds_read_b128 v[148:151], v239
	ds_read_b128 v[152:155], v239 offset:1024
	ds_read_b128 v[156:159], v239 offset:2048
	ds_read_b128 v[160:163], v239 offset:3072
	ds_read_b128 v[164:167], v239 offset:4096
	ds_read_b128 v[168:171], v239 offset:5120
	ds_read_b128 v[172:175], v239 offset:6144
	ds_read_b128 v[196:199], v239 offset:7168
	global_load_lds_dwordx4 v[176:177], off
	v_lshl_add_u64 v[176:177], s[0:1], 0, v[190:191]
	s_add_i32 m0, s89, 0xe000
	s_nop 0
	global_load_lds_dwordx4 v[176:177], off
	s_add_i32 s8, 0, 0x14000
	v_add_u32_e32 v176, s8, v236
	ds_read_b128 v[200:203], v176
	ds_read_b128 v[204:207], v176 offset:1024
	ds_read_b128 v[208:211], v176 offset:2048
	ds_read_b128 v[212:215], v176 offset:3072
	s_waitcnt vmcnt(8)
	s_waitcnt lgkmcnt(0)
	v_mfma_f32_16x16x32_bf16 v[126:129], v[132:135], v[148:151], v[126:129]
	v_mfma_f32_16x16x32_bf16 v[122:125], v[140:143], v[148:151], v[122:125]
	v_mfma_f32_16x16x32_bf16 v[110:113], v[132:135], v[156:159], v[110:113]
	v_mfma_f32_16x16x32_bf16 v[106:109], v[140:143], v[156:159], v[106:109]
	s_barrier
; #define PG8_STAGE(bufoff, gbase, voff) do { _Pragma("unroll") for (int _i = 0; _i < 2; ++_i) \
;         __builtin_amdgcn_global_load_lds((const unsigned*)((const char*)(gbase) + (voff)[_i]), (LAS unsigned*)(lds + (bufoff) + ldsw + _i * 8192), 16, 0, 0); } while (0)
; #define PG8_LDA(dst, b, h) do { _Pragma("unroll") for (int m = 0; m < 4; ++m) _Pragma("unroll") for (int k = 0; k < 2; ++k) dst[m][k] = *(const LAS bf16x8*)(lds + PG8_SA(b, h) + aoff + m * 2048 + k * 1024); } while (0)
; #define PG8_LDB(dst, b, h) do { _Pragma("unroll") for (int n = 0; n < 2; ++n) _Pragma("unroll") for (int k = 0; k < 2; ++k) dst[n][k] = *(const LAS bf16x8*)(lds + PG8_SB(b, h) + boff + n * 2048 + k * 1024); } while (0)
; #define PG8_MMA(ai, bj, At, Bt) do { __builtin_amdgcn_s_setprio(1); _Pragma("unroll") for (int m = 0; m < 4; ++m) _Pragma("unroll") for (int n = 0; n < 2; ++n) _Pragma("unroll") for (int k = 0; k < 2; ++k) \
;         acc[ai][bj][m][n] = __builtin_amdgcn_mfma_f32_16x16x32_bf16(Bt[n][k], At[m][k], acc[ai][bj][m][n], 0, 0, 0); __builtin_amdgcn_s_setprio(0); } while (0)
; #define PG8_WAIT_V(n) asm volatile("s_waitcnt vmcnt(" #n ")" ::: "memory")
; #define PG8_WAIT_L(n) asm volatile("s_waitcnt lgkmcnt(" #n ")" ::: "memory")
; #define PG8_BAR __builtin_amdgcn_s_barrier()
; #define PG8_SCHED __builtin_amdgcn_sched_barrier(0)
; template <class Epi>
; __device__ __forceinline__ void gemm_phase(LAS unsigned char* lds, const Gemm g, const Sched& S, const Epi& E) {
;     ...
;             PG8_LDB(B0, 0, 0); PG8_SCHED; PG8_LDA(At, 0, 0); PG8_STAGE(PG8_SA(1, 1), a1 + hstepA, voffA);
;             PG8_WAIT_L(8); PG8_BAR; PG8_WAIT_L(0); PG8_MMA(0, 0, At, B0); PG8_BAR; PG8_SCHED;
;             PG8_LDB(B1, 0, 1); PG8_STAGE(PG8_SB(0, 0), b2, voffB);
;             PG8_BAR; PG8_WAIT_L(0); PG8_MMA(0, 1, At, B1); PG8_BAR;
;             PG8_LDA(At, 0, 1); PG8_STAGE(PG8_SA(0, 0), a2, voffA);
;             PG8_BAR; PG8_WAIT_L(0); PG8_MMA(1, 0, At, B0); PG8_BAR; PG8_SCHED;
;             PG8_STAGE(PG8_SB(0, 1), b2 + hstepB, voffB);
;             PG8_WAIT_V(6); PG8_BAR; PG8_MMA(1, 1, At, B1); PG8_BAR;
	s_setprio 1
	v_mfma_f32_16x16x32_bf16 v[94:97], v[132:135], v[164:167], v[94:97]
	v_mfma_f32_16x16x32_bf16 v[90:93], v[140:143], v[164:167], v[90:93]
	v_mfma_f32_16x16x32_bf16 v[78:81], v[132:135], v[172:175], v[78:81]
	v_mfma_f32_16x16x32_bf16 v[74:77], v[140:143], v[172:175], v[74:77]
	v_mfma_f32_16x16x32_bf16 v[126:129], v[136:139], v[152:155], v[126:129]
	v_mfma_f32_16x16x32_bf16 v[122:125], v[144:147], v[152:155], v[122:125]
	v_mfma_f32_16x16x32_bf16 v[110:113], v[136:139], v[160:163], v[110:113]
	v_mfma_f32_16x16x32_bf16 v[106:109], v[144:147], v[160:163], v[106:109]
	v_mfma_f32_16x16x32_bf16 v[94:97], v[136:139], v[168:171], v[94:97]
	v_mfma_f32_16x16x32_bf16 v[90:93], v[144:147], v[168:171], v[90:93]
	v_mfma_f32_16x16x32_bf16 v[78:81], v[136:139], v[196:199], v[78:81]
	v_mfma_f32_16x16x32_bf16 v[74:77], v[144:147], v[196:199], v[74:77]
	v_mfma_f32_16x16x32_bf16 v[118:121], v[200:203], v[148:151], v[118:121]
	v_mfma_f32_16x16x32_bf16 v[114:117], v[208:211], v[148:151], v[114:117]
	v_mfma_f32_16x16x32_bf16 v[102:105], v[200:203], v[156:159], v[102:105]
	v_mfma_f32_16x16x32_bf16 v[98:101], v[208:211], v[156:159], v[98:101]
	v_mfma_f32_16x16x32_bf16 v[86:89], v[200:203], v[164:167], v[86:89]
	v_mfma_f32_16x16x32_bf16 v[82:85], v[208:211], v[164:167], v[82:85]
	v_mfma_f32_16x16x32_bf16 v[70:73], v[200:203], v[172:175], v[70:73]
	v_mfma_f32_16x16x32_bf16 v[66:69], v[208:211], v[172:175], v[66:69]
	v_mfma_f32_16x16x32_bf16 v[118:121], v[204:207], v[152:155], v[118:121]
	v_mfma_f32_16x16x32_bf16 v[114:117], v[212:215], v[152:155], v[114:117]
	v_mfma_f32_16x16x32_bf16 v[102:105], v[204:207], v[160:163], v[102:105]
	v_mfma_f32_16x16x32_bf16 v[98:101], v[212:215], v[160:163], v[98:101]
	v_mfma_f32_16x16x32_bf16 v[86:89], v[204:207], v[168:171], v[86:89]
	v_mfma_f32_16x16x32_bf16 v[82:85], v[212:215], v[168:171], v[82:85]
	v_mfma_f32_16x16x32_bf16 v[70:73], v[204:207], v[196:199], v[70:73]
	v_mfma_f32_16x16x32_bf16 v[66:69], v[212:215], v[196:199], v[66:69]
	s_setprio 0
	s_barrier
	s_add_i32 s9, s9, s88
	v_lshl_add_u64 v[176:177], s[86:87], 0, v[180:181]
	s_mov_b32 m0, s9
	v_lshl_add_u64 v[192:193], s[86:87], 0, v[184:185]
	global_load_lds_dwordx4 v[176:177], off
	s_add_i32 m0, s9, 0x2000
	s_nop 0
	global_load_lds_dwordx4 v[192:193], off
	s_mov_b32 m0, s89
	v_lshl_add_u64 v[194:195], s[4:5], 0, v[178:179]
	ds_read_b128 v[148:151], v239 offset:16384
	ds_read_b128 v[152:155], v239 offset:17408
	ds_read_b128 v[156:159], v239 offset:18432
	ds_read_b128 v[160:163], v239 offset:19456
	ds_read_b128 v[164:167], v239 offset:20480
	ds_read_b128 v[168:171], v239 offset:21504
	ds_read_b128 v[172:175], v239 offset:22528
	ds_read_b128 v[196:199], v239 offset:23552
	global_load_lds_dwordx4 v[194:195], off
	v_lshl_add_u64 v[216:217], s[4:5], 0, v[182:183]
	s_mov_b32 m0, s90
	s_nop 0
	global_load_lds_dwordx4 v[216:217], off
	s_add_u32 s56, s86, s36
	s_addc_u32 s57, s87, s37
	s_add_i32 s8, s8, s88
	v_lshl_add_u64 v[222:223], s[56:57], 0, v[180:181]
	s_mov_b32 m0, s8
	v_lshl_add_u64 v[224:225], s[56:57], 0, v[184:185]
	global_load_lds_dwordx4 v[222:223], off
	s_add_i32 m0, s8, 0x2000
	s_nop 0
	global_load_lds_dwordx4 v[224:225], off
	s_waitcnt vmcnt(8)
	s_waitcnt lgkmcnt(0)
	v_mfma_f32_16x16x32_bf16 v[62:65], v[132:135], v[148:151], v[62:65]
	v_mfma_f32_16x16x32_bf16 v[58:61], v[140:143], v[148:151], v[58:61]
	v_mfma_f32_16x16x32_bf16 v[46:49], v[132:135], v[156:159], v[46:49]
	v_mfma_f32_16x16x32_bf16 v[42:45], v[140:143], v[156:159], v[42:45]
	s_barrier
	s_setprio 1
	v_mfma_f32_16x16x32_bf16 v[30:33], v[132:135], v[164:167], v[30:33]
	v_mfma_f32_16x16x32_bf16 v[26:29], v[140:143], v[164:167], v[26:29]
	v_mfma_f32_16x16x32_bf16 v[14:17], v[132:135], v[172:175], v[14:17]
	v_mfma_f32_16x16x32_bf16 v[10:13], v[140:143], v[172:175], v[10:13]
	v_mfma_f32_16x16x32_bf16 v[62:65], v[136:139], v[152:155], v[62:65]
	v_mfma_f32_16x16x32_bf16 v[58:61], v[144:147], v[152:155], v[58:61]
	v_mfma_f32_16x16x32_bf16 v[46:49], v[136:139], v[160:163], v[46:49]
	v_mfma_f32_16x16x32_bf16 v[42:45], v[144:147], v[160:163], v[42:45]
	v_mfma_f32_16x16x32_bf16 v[30:33], v[136:139], v[168:171], v[30:33]
	v_mfma_f32_16x16x32_bf16 v[26:29], v[144:147], v[168:171], v[26:29]
	v_mfma_f32_16x16x32_bf16 v[14:17], v[136:139], v[196:199], v[14:17]
	v_mfma_f32_16x16x32_bf16 v[10:13], v[144:147], v[196:199], v[10:13]
	v_mfma_f32_16x16x32_bf16 v[54:57], v[200:203], v[148:151], v[54:57]
	v_mfma_f32_16x16x32_bf16 v[50:53], v[208:211], v[148:151], v[50:53]
	v_mfma_f32_16x16x32_bf16 v[38:41], v[200:203], v[156:159], v[38:41]
	v_mfma_f32_16x16x32_bf16 v[34:37], v[208:211], v[156:159], v[34:37]
	v_mfma_f32_16x16x32_bf16 v[22:25], v[200:203], v[164:167], v[22:25]
	v_mfma_f32_16x16x32_bf16 v[18:21], v[208:211], v[164:167], v[18:21]
	v_mfma_f32_16x16x32_bf16 v[6:9], v[200:203], v[172:175], v[6:9]
	v_mfma_f32_16x16x32_bf16 v[2:5], v[208:211], v[172:175], v[2:5]
	v_mfma_f32_16x16x32_bf16 v[54:57], v[204:207], v[152:155], v[54:57]
	v_mfma_f32_16x16x32_bf16 v[50:53], v[212:215], v[152:155], v[50:53]
	v_mfma_f32_16x16x32_bf16 v[38:41], v[204:207], v[160:163], v[38:41]
	v_mfma_f32_16x16x32_bf16 v[34:37], v[212:215], v[160:163], v[34:37]
	v_mfma_f32_16x16x32_bf16 v[22:25], v[204:207], v[168:171], v[22:25]
	v_mfma_f32_16x16x32_bf16 v[18:21], v[212:215], v[168:171], v[18:21]
	v_mfma_f32_16x16x32_bf16 v[6:9], v[204:207], v[196:199], v[6:9]
	v_mfma_f32_16x16x32_bf16 v[2:5], v[212:215], v[196:199], v[2:5]
	s_setprio 0
	s_barrier
; #define PG8_STAGE(bufoff, gbase, voff) do { _Pragma("unroll") for (int _i = 0; _i < 2; ++_i) \
;         __builtin_amdgcn_global_load_lds((const unsigned*)((const char*)(gbase) + (voff)[_i]), (LAS unsigned*)(lds + (bufoff) + ldsw + _i * 8192), 16, 0, 0); } while (0)
; #define PG8_LDA(dst, b, h) do { _Pragma("unroll") for (int m = 0; m < 4; ++m) _Pragma("unroll") for (int k = 0; k < 2; ++k) dst[m][k] = *(const LAS bf16x8*)(lds + PG8_SA(b, h) + aoff + m * 2048 + k * 1024); } while (0)
; #define PG8_LDB(dst, b, h) do { _Pragma("unroll") for (int n = 0; n < 2; ++n) _Pragma("unroll") for (int k = 0; k < 2; ++k) dst[n][k] = *(const LAS bf16x8*)(lds + PG8_SB(b, h) + boff + n * 2048 + k * 1024); } while (0)
; #define PG8_MMA(ai, bj, At, Bt) do { __builtin_amdgcn_s_setprio(1); _Pragma("unroll") for (int m = 0; m < 4; ++m) _Pragma("unroll") for (int n = 0; n < 2; ++n) _Pragma("unroll") for (int k = 0; k < 2; ++k) \
;         acc[ai][bj][m][n] = __builtin_amdgcn_mfma_f32_16x16x32_bf16(Bt[n][k], At[m][k], acc[ai][bj][m][n], 0, 0, 0); __builtin_amdgcn_s_setprio(0); } while (0)
; #define PG8_WAIT_L(n) asm volatile("s_waitcnt lgkmcnt(" #n ")" ::: "memory")
; #define PG8_BAR __builtin_amdgcn_s_barrier()
; #define PG8_SCHED __builtin_amdgcn_sched_barrier(0)
; template <class Epi>
; __device__ __forceinline__ void gemm_phase(LAS unsigned char* lds, const Gemm g, const Sched& S, const Epi& E) {
;     ...
;             PG8_LDB(B0, 1, 0); PG8_SCHED; PG8_LDA(At, 1, 0); PG8_STAGE(PG8_SA(0, 1), a2 + hstepA, voffA);
;             PG8_WAIT_L(8); PG8_BAR; PG8_WAIT_L(0); PG8_MMA(0, 0, At, B0); PG8_BAR; PG8_SCHED;
;             PG8_LDB(B1, 1, 1); PG8_STAGE(PG8_SB(1, 0), b3, voffB);
;             PG8_BAR; PG8_WAIT_L(0); PG8_MMA(0, 1, At, B1); PG8_BAR;
	s_add_i32 s8, 0, 0x18000
	v_add_u32_e32 v144, s8, v236
	ds_read_b128 v[132:135], v144
	ds_read_b128 v[136:139], v144 offset:1024
	ds_read_b128 v[140:143], v144 offset:2048
	ds_read_b128 v[144:147], v144 offset:3072
	s_add_u32 s4, s4, s6
	s_addc_u32 s5, s5, s7
	s_mov_b32 m0, s91
	v_lshl_add_u64 v[200:201], s[4:5], 0, v[178:179]
	ds_read_b128 v[148:151], v239 offset:32768
	ds_read_b128 v[152:155], v239 offset:33792
	ds_read_b128 v[156:159], v239 offset:34816
	ds_read_b128 v[160:163], v239 offset:35840
	ds_read_b128 v[164:167], v239 offset:36864
	ds_read_b128 v[168:171], v239 offset:37888
	ds_read_b128 v[172:175], v239 offset:38912
	ds_read_b128 v[196:199], v239 offset:39936
	global_load_lds_dwordx4 v[200:201], off
	v_lshl_add_u64 v[200:201], s[4:5], 0, v[182:183]
	s_mov_b32 m0, s92
	s_nop 0
	global_load_lds_dwordx4 v[200:201], off
	s_add_i32 s4, 0, 0x1c000
	v_add_u32_e32 v212, s4, v236
	ds_read_b128 v[200:203], v212
	ds_read_b128 v[204:207], v212 offset:1024
	ds_read_b128 v[208:211], v212 offset:2048
	ds_read_b128 v[212:215], v212 offset:3072
	s_waitcnt vmcnt(8)
	s_waitcnt lgkmcnt(0)
	v_mfma_f32_16x16x32_bf16 v[126:129], v[132:135], v[148:151], v[126:129]
	v_mfma_f32_16x16x32_bf16 v[122:125], v[140:143], v[148:151], v[122:125]
	v_mfma_f32_16x16x32_bf16 v[110:113], v[132:135], v[156:159], v[110:113]
	v_mfma_f32_16x16x32_bf16 v[106:109], v[140:143], v[156:159], v[106:109]
	s_barrier
	s_setprio 1
	v_mfma_f32_16x16x32_bf16 v[94:97], v[132:135], v[164:167], v[94:97]
	v_mfma_f32_16x16x32_bf16 v[90:93], v[140:143], v[164:167], v[90:93]
	v_mfma_f32_16x16x32_bf16 v[78:81], v[132:135], v[172:175], v[78:81]
	v_mfma_f32_16x16x32_bf16 v[74:77], v[140:143], v[172:175], v[74:77]
	v_mfma_f32_16x16x32_bf16 v[126:129], v[136:139], v[152:155], v[126:129]
	v_mfma_f32_16x16x32_bf16 v[122:125], v[144:147], v[152:155], v[122:125]
	v_mfma_f32_16x16x32_bf16 v[110:113], v[136:139], v[160:163], v[110:113]
	v_mfma_f32_16x16x32_bf16 v[106:109], v[144:147], v[160:163], v[106:109]
	v_mfma_f32_16x16x32_bf16 v[94:97], v[136:139], v[168:171], v[94:97]
	v_mfma_f32_16x16x32_bf16 v[90:93], v[144:147], v[168:171], v[90:93]
	v_mfma_f32_16x16x32_bf16 v[78:81], v[136:139], v[196:199], v[78:81]
	v_mfma_f32_16x16x32_bf16 v[74:77], v[144:147], v[196:199], v[74:77]
	v_mfma_f32_16x16x32_bf16 v[118:121], v[200:203], v[148:151], v[118:121]
	v_mfma_f32_16x16x32_bf16 v[114:117], v[208:211], v[148:151], v[114:117]
	v_mfma_f32_16x16x32_bf16 v[102:105], v[200:203], v[156:159], v[102:105]
	v_mfma_f32_16x16x32_bf16 v[98:101], v[208:211], v[156:159], v[98:101]
	v_mfma_f32_16x16x32_bf16 v[86:89], v[200:203], v[164:167], v[86:89]
	v_mfma_f32_16x16x32_bf16 v[82:85], v[208:211], v[164:167], v[82:85]
	v_mfma_f32_16x16x32_bf16 v[70:73], v[200:203], v[172:175], v[70:73]
	v_mfma_f32_16x16x32_bf16 v[66:69], v[208:211], v[172:175], v[66:69]
	v_mfma_f32_16x16x32_bf16 v[118:121], v[204:207], v[152:155], v[118:121]
	v_mfma_f32_16x16x32_bf16 v[114:117], v[212:215], v[152:155], v[114:117]
	v_mfma_f32_16x16x32_bf16 v[102:105], v[204:207], v[160:163], v[102:105]
	v_mfma_f32_16x16x32_bf16 v[98:101], v[212:215], v[160:163], v[98:101]
	v_mfma_f32_16x16x32_bf16 v[86:89], v[204:207], v[168:171], v[86:89]
	v_mfma_f32_16x16x32_bf16 v[82:85], v[212:215], v[168:171], v[82:85]
	v_mfma_f32_16x16x32_bf16 v[70:73], v[204:207], v[196:199], v[70:73]
	v_mfma_f32_16x16x32_bf16 v[66:69], v[212:215], v[196:199], v[66:69]
	s_setprio 0
	s_barrier
; #define PG8_STAGE(bufoff, gbase, voff) do { _Pragma("unroll") for (int _i = 0; _i < 2; ++_i) \
;         __builtin_amdgcn_global_load_lds((const unsigned*)((const char*)(gbase) + (voff)[_i]), (LAS unsigned*)(lds + (bufoff) + ldsw + _i * 8192), 16, 0, 0); } while (0)
; #define PG8_LDA(dst, b, h) do { _Pragma("unroll") for (int m = 0; m < 4; ++m) _Pragma("unroll") for (int k = 0; k < 2; ++k) dst[m][k] = *(const LAS bf16x8*)(lds + PG8_SA(b, h) + aoff + m * 2048 + k * 1024); } while (0)
; #define PG8_MMA(ai, bj, At, Bt) do { __builtin_amdgcn_s_setprio(1); _Pragma("unroll") for (int m = 0; m < 4; ++m) _Pragma("unroll") for (int n = 0; n < 2; ++n) _Pragma("unroll") for (int k = 0; k < 2; ++k) \
;         acc[ai][bj][m][n] = __builtin_amdgcn_mfma_f32_16x16x32_bf16(Bt[n][k], At[m][k], acc[ai][bj][m][n], 0, 0, 0); __builtin_amdgcn_s_setprio(0); } while (0)
; #define PG8_WAIT_V(n) asm volatile("s_waitcnt vmcnt(" #n ")" ::: "memory")
; #define PG8_WAIT_L(n) asm volatile("s_waitcnt lgkmcnt(" #n ")" ::: "memory")
; #define PG8_BAR __builtin_amdgcn_s_barrier()
; #define PG8_SCHED __builtin_amdgcn_sched_barrier(0)
; template <class Epi>
; __device__ __forceinline__ void gemm_phase(LAS unsigned char* lds, const Gemm g, const Sched& S, const Epi& E) {
;     ...
;             PG8_LDA(At, 1, 1); PG8_STAGE(PG8_SA(1, 0), a3, voffA);
;             PG8_BAR; PG8_WAIT_L(0); PG8_MMA(1, 0, At, B0); PG8_BAR; PG8_SCHED;
;             PG8_STAGE(PG8_SB(1, 1), b3 + hstepB, voffB);
;             PG8_WAIT_V(6); PG8_BAR; PG8_MMA(1, 1, At, B1); PG8_BAR;
;         }
;         E(acc, cur, wr, wc, fr, fq, pre);
;         if (!has_next) break;
;     __device__ __forceinline__ void operator()(const Acc& acc, const Unit& u, int wr, int wc, int fr, int fq, const Pre& pre) const {
;         const int tile = u.pn; int mode = 0; float scale0 = 1.f;
;         if (tile < 36) { const int tg = tile % 12; if (tg < 4) { mode = 1; scale0 = 0.08838834764831845f * LOG2E; } else if (tg < 8) mode = 1; }
;         else if (tile < 40) mode = 1;
;         else if (tile < 44) { mode = 1; scale0 = 0.08838834764831845f; }
;         else if (tile >= 52) mode = 2;
	s_add_i32 s5, s8, s88
	v_lshl_add_u64 v[176:177], v[176:177], 0, s[60:61]
	s_mov_b32 m0, s5
	s_nop 0
	global_load_lds_dwordx4 v[176:177], off
	v_lshl_add_u64 v[176:177], v[192:193], 0, s[60:61]
	s_add_i32 m0, s5, 0x2000
	s_nop 0
	global_load_lds_dwordx4 v[176:177], off
	s_mov_b32 m0, s93
	v_lshl_add_u64 v[176:177], v[194:195], 0, s[60:61]
	ds_read_b128 v[148:151], v239 offset:49152
	ds_read_b128 v[152:155], v239 offset:50176
	ds_read_b128 v[156:159], v239 offset:51200
	ds_read_b128 v[160:163], v239 offset:52224
	ds_read_b128 v[164:167], v239 offset:53248
	ds_read_b128 v[168:171], v239 offset:54272
	ds_read_b128 v[172:175], v239 offset:55296
	ds_read_b128 v[196:199], v239 offset:56320
	global_load_lds_dwordx4 v[176:177], off
	v_lshl_add_u64 v[176:177], v[216:217], 0, s[60:61]
	s_mov_b32 m0, s94
	s_nop 0
	global_load_lds_dwordx4 v[176:177], off
	s_add_i32 s4, s4, s88
	v_lshl_add_u64 v[176:177], v[222:223], 0, s[60:61]
	s_mov_b32 m0, s4
	s_nop 0
	global_load_lds_dwordx4 v[176:177], off
	v_lshl_add_u64 v[176:177], v[224:225], 0, s[60:61]
	s_add_i32 m0, s4, 0x2000
	s_nop 0
	global_load_lds_dwordx4 v[176:177], off
	s_waitcnt vmcnt(8)
	s_waitcnt lgkmcnt(0)
	v_mfma_f32_16x16x32_bf16 v[62:65], v[132:135], v[148:151], v[62:65]
	v_mfma_f32_16x16x32_bf16 v[58:61], v[140:143], v[148:151], v[58:61]
	v_mfma_f32_16x16x32_bf16 v[46:49], v[132:135], v[156:159], v[46:49]
	v_mfma_f32_16x16x32_bf16 v[42:45], v[140:143], v[156:159], v[42:45]
	s_barrier
	s_setprio 1
	v_mfma_f32_16x16x32_bf16 v[30:33], v[132:135], v[164:167], v[30:33]
	v_mfma_f32_16x16x32_bf16 v[26:29], v[140:143], v[164:167], v[26:29]
	v_mfma_f32_16x16x32_bf16 v[14:17], v[132:135], v[172:175], v[14:17]
	v_mfma_f32_16x16x32_bf16 v[10:13], v[140:143], v[172:175], v[10:13]
	v_mfma_f32_16x16x32_bf16 v[62:65], v[136:139], v[152:155], v[62:65]
	v_mfma_f32_16x16x32_bf16 v[58:61], v[144:147], v[152:155], v[58:61]
	v_mfma_f32_16x16x32_bf16 v[46:49], v[136:139], v[160:163], v[46:49]
	v_mfma_f32_16x16x32_bf16 v[42:45], v[144:147], v[160:163], v[42:45]
	v_mfma_f32_16x16x32_bf16 v[30:33], v[136:139], v[168:171], v[30:33]
	v_mfma_f32_16x16x32_bf16 v[26:29], v[144:147], v[168:171], v[26:29]
	v_mfma_f32_16x16x32_bf16 v[14:17], v[136:139], v[196:199], v[14:17]
	v_mfma_f32_16x16x32_bf16 v[10:13], v[144:147], v[196:199], v[10:13]
	v_mfma_f32_16x16x32_bf16 v[54:57], v[200:203], v[148:151], v[54:57]
	v_mfma_f32_16x16x32_bf16 v[50:53], v[208:211], v[148:151], v[50:53]
	v_mfma_f32_16x16x32_bf16 v[38:41], v[200:203], v[156:159], v[38:41]
	v_mfma_f32_16x16x32_bf16 v[34:37], v[208:211], v[156:159], v[34:37]
	v_mfma_f32_16x16x32_bf16 v[22:25], v[200:203], v[164:167], v[22:25]
	v_mfma_f32_16x16x32_bf16 v[18:21], v[208:211], v[164:167], v[18:21]
	v_mfma_f32_16x16x32_bf16 v[6:9], v[200:203], v[172:175], v[6:9]
	v_mfma_f32_16x16x32_bf16 v[2:5], v[208:211], v[172:175], v[2:5]
	v_mfma_f32_16x16x32_bf16 v[54:57], v[204:207], v[152:155], v[54:57]
	v_mfma_f32_16x16x32_bf16 v[50:53], v[212:215], v[152:155], v[50:53]
	v_mfma_f32_16x16x32_bf16 v[38:41], v[204:207], v[160:163], v[38:41]
	v_mfma_f32_16x16x32_bf16 v[34:37], v[212:215], v[160:163], v[34:37]
	v_mfma_f32_16x16x32_bf16 v[22:25], v[204:207], v[168:171], v[22:25]
	v_mfma_f32_16x16x32_bf16 v[18:21], v[212:215], v[168:171], v[18:21]
	v_mfma_f32_16x16x32_bf16 v[6:9], v[204:207], v[196:199], v[6:9]
	v_mfma_f32_16x16x32_bf16 v[2:5], v[212:215], v[196:199], v[2:5]
	s_setprio 0
	s_add_u32 s0, s0, 0x100
	s_addc_u32 s1, s1, 0
	s_add_u32 s34, s34, 0x100
	s_addc_u32 s35, s35, 0
	s_cmp_ge_u32 s14, s73
	s_mov_b32 s4, s14
	s_barrier
	s_cbranch_scc0 .LBB0_649
	v_readfirstlane_b32 s98, v219
	s_nop 1
	s_bitcmp1_b32 s98, 8
	s_cbranch_scc1 .Lresync_x_649
	s_barrier
.Lresync_x_649:
	s_cmp_gt_i32 s3, 35
	s_cbranch_scc0 .LBB0_652
	s_cmp_gt_u32 s3, 51
	s_cselect_b32 s8, 2, 0
	s_cmp_gt_u32 s3, 39
	s_cselect_b64 s[0:1], -1, 0
	s_cmp_lt_u32 s3, 44
	s_cselect_b64 s[14:15], -1, 0
	s_and_b64 s[4:5], s[14:15], exec
	s_cselect_b32 s4, 1, s8
	s_and_b64 vcc, s[0:1], s[14:15]
	v_mov_b32_e32 v132, 0x3db504f3
	v_cndmask_b32_e32 v240, 1.0, v132, vcc
	v_mov_b32_e32 v132, s4
	s_cbranch_execz .LBB0_653
	s_branch .LBB0_654

; #define PG8_WAIT_V(n) asm volatile("s_waitcnt vmcnt(" #n ")" ::: "memory")
; #define PG8_BAR __builtin_amdgcn_s_barrier()
; template <class Epi>
; __device__ __forceinline__ void gemm_phase(LAS unsigned char* lds, const Gemm g, const Sched& S, const Epi& E) {
;     ...
;     PG8_WAIT_V(0);
;     if (wr == 0) PG8_BAR;
;     PG8_BAR;
.LBB0_691:
	s_waitcnt vmcnt(0)
	v_readlane_b32 s0, v254, 29
	v_readlane_b32 s90, v254, 39
	s_cmpk_gt_u32 s0, 0xff
	v_readlane_b32 s96, v253, 48
	s_mov_b32 s97, 0x800000
	v_readlane_b32 s91, v254, 40
	s_cbranch_scc1 .LBB0_693
.LBB0_693:
	s_mov_b32 s39, s67
	v_readlane_b32 s82, v254, 43
	v_readlane_b32 s66, v254, 45
	v_readlane_b32 s83, v254, 44
	v_readlane_b32 s57, v254, 37
	v_readlane_b32 s67, v254, 46
	s_barrier

; #define LAS __attribute__((address_space(3)))
;     __device__ __forceinline__ bool next(int i, Unit& u) const {
;         const long L = (long)i * G + c; if (L >= total) return false;
;         const int z = (int)(L / per); int wgid = (int)(L % per);
;         { const int q = per / NXCD, r = per % NXCD, xcd = wgid % NXCD, off = wgid / NXCD; wgid = (xcd < r ? xcd * (q + 1) : r * (q + 1) + (xcd - r) * q) + off; }
;         const int nig = WGM * nN, gid = wgid / nig, fm = gid * WGM, gsz = (nM - fm) < WGM ? (nM - fm) : WGM;
;         u.pm = fm + ((wgid % nig) % gsz); u.pn = (wgid % nig) / gsz; u.zb = z / nh; u.zh = z % nh;
;         u.ao = u.zb * sAb + u.zh * sAh + u.pm * tA; u.bo = u.zb * sBb + u.zh * sBh + u.pn * tB; return true;
;     }
; template <class Epi>
; __device__ __forceinline__ void gemm_phase(LAS unsigned char* lds, const Gemm g, const Sched& S, const Epi& E) {
;     const int tid = otid(), wid = __builtin_amdgcn_readfirstlane(tid >> 6), lane = tid & 63, wr = wid >> 2, wc = wid & 3, fr = lane & 15, fq = lane >> 4;
;     const int nt = g.K / BK;
;     unsigned voffA[2], voffB[2];
; #pragma unroll
;     for (int i = 0; i < 2; ++i) { int R, C; stage_rc(tid * 16 + i * 8192, R, C); const int Rb = Epi::PERM ? ((R & ~31) + perm32(R & 31)) : R;
;         voffA[i] = (unsigned)(R * g.lda + C) * 2u; voffB[i] = (unsigned)(Rb * g.ldb + C) * 2u; }
;     const size_t kstep = (size_t)(BK * 2);
;     const size_t hstepA = (size_t)HALF * g.lda * 2, hstepB = (size_t)HALF * g.ldb * 2;
;     const unsigned ldsw = (unsigned)wid * 1024u;
;     const int aoff = lds_byte(wr * 64 + fr, fq * 8), boff = lds_byte(wc * 32 + fr, fq * 8);
;     ...
;     Unit cur, nxt; int ui = 0;
;     if (!S.next(0, cur)) return;
;     f32x4 acc[2][2][4][2];
; #pragma unroll
;     for (int a = 0; a < 2; ++a)
; #pragma unroll
;         for (int b = 0; b < 2; ++b)
; #pragma unroll
;             for (int m = 0; m < 4; ++m)
; #pragma unroll
;                 for (int n = 0; n < 2; ++n) acc[a][b][m][n] = (f32x4){0.f, 0.f, 0.f, 0.f};
;     bf16x8 At[4][2], B0[2][2], B1[2][2];
;     const char* cA = (const char*)g.A + cur.ao; const char* cB = (const char*)g.Bt + cur.bo;
;     PG8_STAGE(PG8_SB(0, 0), cB, voffB); PG8_STAGE(PG8_SA(0, 0), cA, voffA); PG8_STAGE(PG8_SB(0, 1), cB + hstepB, voffB); PG8_STAGE(PG8_SA(0, 1), cA + hstepA, voffA);
.LBB0_810:
	s_waitcnt lgkmcnt(0)
	v_bfe_i32 v3, v20, 27, 1
	v_lshlrev_b32_e32 v2, 4, v20
	v_lshrrev_b32_e32 v3, 22, v3
	v_add_u32_e32 v3, v2, v3
	v_and_b32_e32 v3, 0xfffffc00, v3
	s_add_i32 s6, s14, 1
	v_ashrrev_i32_e32 v0, 31, v20
	v_sub_u32_e32 v3, v2, v3
	s_and_b64 s[0:1], s[0:1], exec
	v_lshrrev_b32_e32 v0, 26, v0
	v_lshrrev_b32_e32 v4, 4, v3
	s_cselect_b32 s6, s6, s14
	v_add_u32_e32 v0, v20, v0
	v_bitop3_b32 v4, v4, v3, 32 bitop3:0x6c
	v_ashrrev_i32_e32 v3, 31, v3
	s_add_i32 s7, s6, 1
	v_ashrrev_i32_e32 v0, 6, v0
	v_lshrrev_b32_e32 v3, 26, v3
	s_and_b64 s[0:1], s[4:5], exec
	v_lshlrev_b32_e32 v5, 3, v0
	v_add_u32_e32 v3, v4, v3
	s_cselect_b32 s0, s7, s6
	v_and_b32_e32 v5, -16, v5
	v_ashrrev_i32_e32 v3, 6, v3
	v_lshlrev_b32_e32 v0, 5, v0
	s_xor_b32 s0, s0, s42
	v_add_u32_e32 v5, v3, v5
	v_and_b32_e32 v14, 32, v0
	v_mul_i32_i24_e32 v0, 64, v3
	s_sub_i32 s4, s0, s42
	v_sub_u32_e32 v0, v4, v0
	v_mov_b32_e32 v7, 1
	v_lshlrev_b32_e32 v4, 1, v5
	v_lshrrev_b32_e32 v6, 2, v5
	v_and_b32_e32 v3, 3, v3
	s_mov_b32 s0, 0x7fffffe0
	v_ashrrev_i16_sdwa v0, v7, sext(v0) dst_sel:DWORD dst_unused:UNUSED_PAD src0_sel:DWORD src1_sel:BYTE_0
	v_and_b32_e32 v4, 24, v4
	v_and_b32_e32 v6, 4, v6
	v_and_or_b32 v3, v5, s0, v3
	v_bfe_i32 v15, v0, 0, 16
	v_or3_b32 v3, v3, v6, v4
	v_add_u32_e32 v0, v14, v15
	v_mul_lo_u32 v16, v5, s82
	v_mul_lo_u32 v3, v3, s66
	v_add_u32_e32 v2, 0x2000, v2
	v_add_lshl_u32 v130, v0, v16, 1
	v_add_lshl_u32 v0, v3, v0, 1
	v_ashrrev_i32_e32 v3, 31, v2
	v_lshrrev_b32_e32 v3, 22, v3
	v_add_u32_e32 v3, v2, v3
	v_ashrrev_i32_e32 v3, 10, v3
	v_mul_i32_i24_e32 v4, 0x400, v3
	v_sub_u32_e32 v2, v2, v4
	v_lshrrev_b32_e32 v4, 4, v2
	v_bitop3_b32 v2, v4, v2, 32 bitop3:0x6c
	v_ashrrev_i32_e32 v5, 31, v2
	v_lshrrev_b32_e32 v5, 26, v5
	v_lshlrev_b32_e32 v4, 3, v3
	v_add_u32_e32 v5, v2, v5
	v_and_b32_e32 v4, -16, v4
	v_ashrrev_i32_e32 v6, 6, v5
	v_lshlrev_b32_e32 v3, 5, v3
	v_add_u32_e32 v4, v6, v4
	v_and_b32_e32 v17, 32, v3
	v_and_b32_e32 v3, 0xc0, v5
	v_sub_u32_e32 v2, v2, v3
	v_lshlrev_b32_e32 v3, 1, v4
	v_lshrrev_b32_e32 v5, 2, v4
	v_and_b32_e32 v6, 3, v6
	v_ashrrev_i16_sdwa v2, v7, sext(v2) dst_sel:DWORD dst_unused:UNUSED_PAD src0_sel:DWORD src1_sel:BYTE_0
	v_and_b32_e32 v3, 24, v3
	v_and_b32_e32 v5, 4, v5
	v_and_or_b32 v6, v4, s0, v6
	v_bfe_i32 v18, v2, 0, 16
	v_or3_b32 v3, v6, v5, v3
	v_readlane_b32 s8, v254, 5
	v_add_u32_e32 v2, v17, v18
	v_mul_lo_u32 v3, v3, s66
	s_mul_i32 s74, s8, s57
	v_add_lshl_u32 v134, v3, v2, 1
	v_cvt_f32_i32_e32 v3, s74
	s_add_i32 s27, s27, s3
	v_mul_lo_u32 v19, v4, s82
	s_sext_i32_i16 s0, s27
	v_add_lshl_u32 v132, v2, v19, 1
	v_cvt_f32_i32_e32 v2, s0
	v_rcp_iflag_f32_e32 v4, v3
	s_xor_b32 s3, s0, s74
	s_ashr_i32 s1, s2, 6
	s_ashr_i32 s3, s3, 30
	v_mul_f32_e32 v4, v2, v4
	v_trunc_f32_e32 v4, v4
	v_fma_f32 v2, -v4, v3, v2
	v_cvt_i32_f32_e32 v4, v4
	s_ashr_i32 s24, s2, 8
	s_lshl_b64 s[6:7], s[82:83], 8
	s_lshl_b64 s[14:15], s[66:67], 8
	s_lshl_b32 s51, s1, 10
	s_or_b32 s3, s3, 1
	v_cmp_ge_f32_e64 s[34:35], |v2|, |v3|
	s_and_b64 s[34:35], s[34:35], exec
	s_cselect_b32 s0, s3, 0
	v_readfirstlane_b32 s3, v4
	s_add_i32 s0, s3, s0
	s_sext_i32_i16 s3, s0
	s_mul_i32 s3, s8, s3
	v_readlane_b32 s5, v253, 63
	s_sub_i32 s5, s5, s3
	s_min_i32 s5, s5, s8
	s_sext_i32_i16 s33, s5
	v_cvt_f32_i32_e32 v3, s33
	s_mul_i32 s0, s0, s74
	s_sub_i32 s27, s27, s0
	s_sext_i32_i16 s0, s27
	v_cvt_f32_i32_e32 v2, s0
	v_rcp_iflag_f32_e32 v4, v3
	s_xor_b32 s34, s0, s33
	s_ashr_i32 s34, s34, 30
	s_or_b32 s36, s34, 1
	v_mul_f32_e32 v4, v2, v4
	v_trunc_f32_e32 v4, v4
	v_fma_f32 v2, -v4, v3, v2
	v_cmp_ge_f32_e64 s[34:35], |v2|, |v3|
	v_cvt_f32_u32_e32 v2, s25
	v_cvt_i32_f32_e32 v4, v4
	s_and_b64 s[34:35], s[34:35], exec
	s_cselect_b32 s0, s36, 0
	v_rcp_iflag_f32_e32 v2, v2
	v_readfirstlane_b32 s33, v4
	s_add_i32 s0, s33, s0
	s_mul_i32 s5, s0, s5
	v_mul_f32_e32 v2, 0x4f7ffffe, v2
	v_cvt_u32_f32_e32 v2, v2
	s_sub_i32 s5, s27, s5
	s_sext_i32_i16 s5, s5
	s_add_i32 s81, s3, s5
	s_sub_i32 s3, 0, s25
	v_readfirstlane_b32 s33, v2
	s_mul_i32 s3, s3, s33
	s_mul_hi_u32 s3, s33, s3
	s_abs_i32 s27, s4
	s_add_i32 s3, s33, s3
	s_mul_hi_u32 s33, s27, s3
	s_mul_i32 s34, s33, s25
	s_sub_i32 s27, s27, s34
	s_ashr_i32 s5, s4, 31
	s_add_i32 s34, s33, 1
	s_sub_i32 s35, s27, s25
	s_cmp_ge_u32 s27, s25
	s_cselect_b32 s33, s34, s33
	s_cselect_b32 s27, s35, s27
	s_add_i32 s34, s33, 1
	s_cmp_ge_u32 s27, s25
	s_cselect_b32 s27, s34, s33
	s_xor_b32 s27, s27, s5
	s_sub_i32 s27, s27, s5
	s_mul_i32 s5, s27, s25
	s_sub_i32 s33, s4, s5
	s_ashr_i32 s34, s33, 31
	s_mul_i32 s4, s22, s34
	s_mul_hi_u32 s5, s22, s33
	s_add_i32 s4, s5, s4
	s_mul_i32 s5, s23, s33
	s_ashr_i32 s37, s27, 31
	s_add_i32 s35, s4, s5
	s_mul_i32 s4, s18, s37
	s_mul_hi_u32 s5, s18, s27
	s_add_i32 s4, s5, s4
	s_mul_i32 s5, s19, s27
	s_add_i32 s38, s4, s5
	s_bfe_i64 s[4:5], s[0:1], 0x100000
	s_mul_i32 s5, s30, s5
	s_mul_hi_u32 s40, s30, s4
	s_add_i32 s5, s40, s5
	s_mul_i32 s40, s31, s4
	s_add_i32 s5, s5, s40
	s_mul_i32 s34, s20, s34
	s_mul_hi_u32 s40, s20, s33
	s_add_i32 s34, s40, s34
	s_mul_i32 s40, s21, s33
	s_mul_i32 s36, s22, s33
	s_add_i32 s34, s34, s40
	s_mul_i32 s40, s20, s33
	s_mul_i32 s33, s16, s37
	s_mul_hi_u32 s37, s16, s27
	s_add_i32 s33, s37, s33
	s_mul_i32 s37, s17, s27
	s_add_i32 s37, s33, s37
	s_ashr_i32 s33, s81, 31
	s_mul_i32 s33, s28, s33
	s_mul_hi_u32 s41, s28, s81
	s_add_i32 s33, s41, s33
	s_mul_i32 s41, s29, s81
	s_add_i32 s41, s33, s41
	s_add_u32 s33, s10, s36
	s_mul_i32 s39, s18, s27
	s_addc_u32 s35, s11, s35
	s_add_u32 s33, s33, s39
	s_mul_i32 s4, s30, s4
	s_addc_u32 s35, s35, s38
	s_add_u32 s68, s33, s4
	s_addc_u32 s69, s35, s5
	s_add_i32 s33, s51, 0
	s_add_i32 m0, s33, 0x10000
	v_readlane_b32 s4, v254, 11
	global_load_lds_dwordx4 v0, s[68:69]
	s_add_i32 m0, s33, 0x12000
	v_readlane_b32 s5, v254, 12
	s_add_u32 s4, s4, s40
	s_mul_i32 s27, s16, s27
	s_addc_u32 s5, s5, s34
	s_add_u32 s4, s4, s27
	s_mul_i32 s48, s28, s81
	s_addc_u32 s5, s5, s37
	s_add_u32 s4, s4, s48
	global_load_lds_dwordx4 v134, s[68:69]
	s_addc_u32 s5, s5, s41
	s_mov_b32 m0, s33
	s_add_i32 s48, s33, 0x2000
	global_load_lds_dwordx4 v130, s[4:5]
	s_mov_b32 m0, s48
	s_add_u32 s34, s68, s14
	global_load_lds_dwordx4 v132, s[4:5]
	s_addc_u32 s35, s69, s15
	s_add_i32 m0, s33, 0x14000
	v_mov_b32_e32 v135, v1
	global_load_lds_dwordx4 v0, s[34:35]
	s_add_i32 m0, s33, 0x16000
	v_lshl_add_u64 v[10:11], s[34:35], 0, v[0:1]
	v_lshl_add_u64 v[12:13], s[34:35], 0, v[134:135]
	global_load_lds_dwordx4 v134, s[34:35]
	s_add_u32 s34, s4, s6
	s_addc_u32 s35, s5, s7
	s_add_i32 s58, s33, 0x4000
	s_mov_b32 m0, s58
	s_add_i32 s72, s33, 0x6000
	global_load_lds_dwordx4 v130, s[34:35]
	s_mov_b32 m0, s72
	v_mov_b32_e32 v131, v1
	global_load_lds_dwordx4 v132, s[34:35]
	v_mov_b32_e32 v133, v1
	v_lshl_add_u64 v[2:3], s[68:69], 0, v[0:1]
	v_lshl_add_u64 v[4:5], s[68:69], 0, v[134:135]
	v_lshl_add_u64 v[6:7], s[4:5], 0, v[130:131]
	v_lshl_add_u64 v[8:9], s[4:5], 0, v[132:133]
	s_cmp_lg_u32 s24, 1
	s_cbranch_scc1 .LBB0_812
; #define PG8_STAGE(bufoff, gbase, voff) do { _Pragma("unroll") for (int _i = 0; _i < 2; ++_i) \
;         __builtin_amdgcn_global_load_lds((const unsigned*)((const char*)(gbase) + (voff)[_i]), (LAS unsigned*)(lds + (bufoff) + ldsw + _i * 8192), 16, 0, 0); } while (0)
; #define PG8_WAIT_V(n) asm volatile("s_waitcnt vmcnt(" #n ")" ::: "memory")
; #define PG8_BAR __builtin_amdgcn_s_barrier()
;     __device__ __forceinline__ Pre prefetch(const Unit& u, int wr, int fr) const { return pre_rows(ss, u.pm * 256 + wr * 64 + (int)(threadIdx.x & 63)); }
;     __device__ __forceinline__ Pre prefetch(const Unit& u, int wr, int fr) const { return pre_rows(ss, u.pm * 256 + wr * 64 + (int)(threadIdx.x & 63)); }
;     __device__ __forceinline__ Pre prefetch(const Unit& u, int wr, int fr) const { return pre_rows(ss, u.zb * zrow + u.pm * 256 + wr * 64 + (int)(threadIdx.x & 63)); }
; template <class Epi>
; __device__ __forceinline__ void gemm_phase(LAS unsigned char* lds, const Gemm g, const Sched& S, const Epi& E) {
;     ...
;     const char* cA = (const char*)g.A + cur.ao; const char* cB = (const char*)g.Bt + cur.bo;
;     PG8_STAGE(PG8_SB(0, 0), cB, voffB); PG8_STAGE(PG8_SA(0, 0), cA, voffA); PG8_STAGE(PG8_SB(0, 1), cB + hstepB, voffB); PG8_STAGE(PG8_SA(0, 1), cA + hstepA, voffA);
;     if (wr == 1) PG8_BAR;
;     PG8_WAIT_V(4); PG8_BAR;
;     PG8_STAGE(PG8_SB(1, 0), cB + kstep, voffB); PG8_STAGE(PG8_SA(1, 0), cA + kstep, voffA); PG8_STAGE(PG8_SB(1, 1), cB + hstepB + kstep, voffB);
;     PG8_WAIT_V(6); PG8_BAR;
;     for (;;) {
;         const Pre pre = E.prefetch(cur, wr, fr);
;         const bool has_next = S.next(ui + 1, nxt);
;         const char* nA = has_next ? (const char*)g.A + nxt.ao : cA; const char* nB = has_next ? (const char*)g.Bt + nxt.bo : cB;
;     __device__ __forceinline__ Pre prefetch(const Unit& u, int wr, int fr) const { return pre_rows(ss, u.pm * 256 + wr * 64 + (int)(threadIdx.x & 63)); }
.LBB0_812:
	s_add_i32 m0, s33, 0x18000
	v_lshl_add_u64 v[2:3], v[2:3], 0, s[60:61]
	s_waitcnt vmcnt(0)
	s_barrier
	global_load_lds_dwordx4 v[2:3], off
	v_lshl_add_u64 v[2:3], v[4:5], 0, s[60:61]
	s_add_i32 m0, s33, 0x1a000
	s_add_i32 s75, s33, 0x8000
	global_load_lds_dwordx4 v[2:3], off
	v_lshl_add_u64 v[2:3], v[6:7], 0, s[60:61]
	s_mov_b32 m0, s75
	s_add_i32 s76, s33, 0xa000
	global_load_lds_dwordx4 v[2:3], off
	v_lshl_add_u64 v[2:3], v[8:9], 0, s[60:61]
	s_mov_b32 m0, s76
	s_sext_i32_i16 s55, s0
	global_load_lds_dwordx4 v[2:3], off
	s_add_i32 m0, s33, 0x1c000
	v_lshl_add_u64 v[2:3], v[10:11], 0, s[60:61]
	global_load_lds_dwordx4 v[2:3], off
	v_lshl_add_u64 v[2:3], v[12:13], 0, s[60:61]
	s_add_i32 m0, s33, 0x1e000
	s_lshl_b32 s0, s24, 6
	global_load_lds_dwordx4 v[2:3], off
	v_and_b32_e32 v2, 63, v219
	v_or_b32_e32 v147, s0, v2
	v_cvt_f32_u32_e32 v2, s74
	v_lshrrev_b32_e32 v21, 1, v20
	v_and_b32_e32 v21, 24, v21
	v_and_b32_e32 v141, 15, v20
	v_rcp_iflag_f32_e32 v2, v2
	v_lshlrev_b32_e32 v22, 1, v21
	v_lshlrev_b32_e32 v20, 2, v20
	s_lshl_b32 s1, s1, 5
	v_mul_f32_e32 v2, 0x4f7ffffe, v2
	v_cvt_u32_f32_e32 v2, v2
	v_lshl_or_b32 v22, v141, 6, v22
	s_lshl_b32 s24, s24, 13
	v_and_b32_e32 v20, 32, v20
	s_and_b32 s1, s1, 0x60
	v_readlane_b32 s36, v253, 61
	v_bitop3_b32 v23, v22, s24, v20 bitop3:0xde
	s_lshl_b32 s24, s1, 7
	s_add_i32 s77, s73, -2
	v_readlane_b32 s37, v253, 62
	s_cmp_eq_u64 s[36:37], 0
	s_cselect_b64 s[34:35], -1, 0
	s_cmp_lg_u64 s[36:37], 0
	v_or_b32_e32 v149, s1, v21
	v_readfirstlane_b32 s1, v2
	v_add_u32_e32 v2, v16, v14
	v_or_b32_e32 v143, s0, v141
	s_cselect_b64 s[36:37], -1, 0
	s_sub_i32 s0, 0, s74
	v_add_lshl_u32 v2, v2, v15, 1
	v_mov_b32_e32 v3, v1
	s_waitcnt vmcnt(6)
	s_mul_i32 s0, s0, s1
	v_lshl_add_u64 v[136:137], s[6:7], 0, v[2:3]
	v_add_u32_e32 v2, v19, v17
	s_mul_hi_u32 s0, s1, s0
	v_add_lshl_u32 v2, v2, v18, 1
	v_bitop3_b32 v145, v22, s24, v20 bitop3:0xde
	s_mov_b32 s27, s9
	s_mov_b32 s24, 0
	s_add_i32 s78, s1, s0
	v_lshl_add_u64 v[138:139], s[6:7], 0, v[2:3]
	v_add_u32_e32 v151, 0, v23
	s_barrier

; #define PG8_STAGE(bufoff, gbase, voff) do { _Pragma("unroll") for (int _i = 0; _i < 2; ++_i) \
;         __builtin_amdgcn_global_load_lds((const unsigned*)((const char*)(gbase) + (voff)[_i]), (LAS unsigned*)(lds + (bufoff) + ldsw + _i * 8192), 16, 0, 0); } while (0)
; #define PG8_LDA(dst, b, h) do { _Pragma("unroll") for (int m = 0; m < 4; ++m) _Pragma("unroll") for (int k = 0; k < 2; ++k) dst[m][k] = *(const LAS bf16x8*)(lds + PG8_SA(b, h) + aoff + m * 2048 + k * 1024); } while (0)
; #define PG8_LDB(dst, b, h) do { _Pragma("unroll") for (int n = 0; n < 2; ++n) _Pragma("unroll") for (int k = 0; k < 2; ++k) dst[n][k] = *(const LAS bf16x8*)(lds + PG8_SB(b, h) + boff + n * 2048 + k * 1024); } while (0)
; #define PG8_MMA(ai, bj, At, Bt) do { __builtin_amdgcn_s_setprio(1); _Pragma("unroll") for (int m = 0; m < 4; ++m) _Pragma("unroll") for (int n = 0; n < 2; ++n) _Pragma("unroll") for (int k = 0; k < 2; ++k) \
;         acc[ai][bj][m][n] = __builtin_amdgcn_mfma_f32_16x16x32_bf16(Bt[n][k], At[m][k], acc[ai][bj][m][n], 0, 0, 0); __builtin_amdgcn_s_setprio(0); } while (0)
; #define PG8_WAIT_L(n) asm volatile("s_waitcnt lgkmcnt(" #n ")" ::: "memory")
; #define PG8_BAR __builtin_amdgcn_s_barrier()
; #define PG8_SCHED __builtin_amdgcn_sched_barrier(0)
; template <class Epi>
; __device__ __forceinline__ void gemm_phase(LAS unsigned char* lds, const Gemm g, const Sched& S, const Epi& E) {
;     ...
;         const bool has_next = S.next(ui + 1, nxt);
;         const char* nA = has_next ? (const char*)g.A + nxt.ao : cA; const char* nB = has_next ? (const char*)g.Bt + nxt.bo : cB;
;         for (int t = 0; t < nt; t += 2) {
;             const bool last = (t == nt - 2);
;             const char* a1 = cA + (size_t)(t + 1) * kstep;
;             const char* a2 = last ? nA : cA + (size_t)(t + 2) * kstep; const char* b2 = last ? nB : cB + (size_t)(t + 2) * kstep;
;             const char* a3 = a2 + kstep; const char* b3 = b2 + kstep;
;             PG8_LDB(B0, 0, 0); PG8_SCHED; PG8_LDA(At, 0, 0); PG8_STAGE(PG8_SA(1, 1), a1 + hstepA, voffA);
;             PG8_WAIT_L(8); PG8_BAR; PG8_WAIT_L(0); PG8_MMA(0, 0, At, B0); PG8_BAR; PG8_SCHED;
;             PG8_LDB(B1, 0, 1); PG8_STAGE(PG8_SB(0, 0), b2, voffB);
;             PG8_BAR; PG8_WAIT_L(0); PG8_MMA(0, 1, At, B1); PG8_BAR;
;     ...
;                     for (int n = 0; n < 2; ++n) acc[a][b][m][n] = (f32x4){0.f, 0.f, 0.f, 0.f};
.LBB0_824:
	v_mov_b64_e32 v[2:3], s[26:27]
	v_cmp_lt_i64_e32 vcc, s[64:65], v[2:3]
	v_readlane_b32 s64, v254, 11
	v_readlane_b32 s65, v254, 12
	s_add_u32 s64, s64, s38
	s_addc_u32 s65, s65, s39
	s_and_b64 s[66:67], vcc, exec
	s_cselect_b32 s57, s65, s5
	s_cselect_b32 s59, s64, s4
	s_add_u32 s66, s10, s40
	s_addc_u32 s67, s11, s41
	s_and_b64 s[70:71], vcc, exec
	s_cselect_b32 s82, s67, s69
	s_cselect_b32 s83, s66, s68
	s_add_u32 s4, s4, 0x80
	s_addc_u32 s5, s5, 0
	s_add_u32 s84, s68, 0x100
	v_mov_b32_e32 v2, 0
	s_addc_u32 s85, s69, 0
	s_mov_b32 s68, 0
	v_mov_b32_e32 v3, v2
	v_mov_b32_e32 v4, v2
	v_mov_b32_e32 v5, v2
	v_mov_b32_e32 v6, v2
	v_mov_b32_e32 v7, v2
	v_mov_b32_e32 v8, v2
	v_mov_b32_e32 v9, v2
	v_mov_b32_e32 v18, v2
	v_mov_b32_e32 v19, v2
	v_mov_b32_e32 v20, v2
	v_mov_b32_e32 v21, v2
	v_mov_b32_e32 v22, v2
	v_mov_b32_e32 v23, v2
	v_mov_b32_e32 v24, v2
	v_mov_b32_e32 v25, v2
	v_mov_b32_e32 v34, v2
	v_mov_b32_e32 v35, v2
	v_mov_b32_e32 v36, v2
	v_mov_b32_e32 v37, v2
	v_mov_b32_e32 v38, v2
	v_mov_b32_e32 v39, v2
	v_mov_b32_e32 v40, v2
	v_mov_b32_e32 v41, v2
	v_mov_b32_e32 v50, v2
	v_mov_b32_e32 v51, v2
	v_mov_b32_e32 v52, v2
	v_mov_b32_e32 v53, v2
	v_mov_b32_e32 v54, v2
	v_mov_b32_e32 v55, v2
	v_mov_b32_e32 v56, v2
	v_mov_b32_e32 v57, v2
	v_mov_b32_e32 v10, v2
	v_mov_b32_e32 v11, v2
	v_mov_b32_e32 v12, v2
	v_mov_b32_e32 v13, v2
	v_mov_b32_e32 v14, v2
	v_mov_b32_e32 v15, v2
	v_mov_b32_e32 v16, v2
	v_mov_b32_e32 v17, v2
	v_mov_b32_e32 v26, v2
	v_mov_b32_e32 v27, v2
	v_mov_b32_e32 v28, v2
	v_mov_b32_e32 v29, v2
	v_mov_b32_e32 v30, v2
	v_mov_b32_e32 v31, v2
	v_mov_b32_e32 v32, v2
	v_mov_b32_e32 v33, v2
	v_mov_b32_e32 v42, v2
	v_mov_b32_e32 v43, v2
	v_mov_b32_e32 v44, v2
	v_mov_b32_e32 v45, v2
	v_mov_b32_e32 v46, v2
	v_mov_b32_e32 v47, v2
	v_mov_b32_e32 v48, v2
	v_mov_b32_e32 v49, v2
	v_mov_b32_e32 v58, v2
	v_mov_b32_e32 v59, v2
	v_mov_b32_e32 v60, v2
	v_mov_b32_e32 v61, v2
	v_mov_b32_e32 v62, v2
	v_mov_b32_e32 v63, v2
	v_mov_b32_e32 v64, v2
	v_mov_b32_e32 v65, v2
	v_mov_b32_e32 v66, v2
	v_mov_b32_e32 v67, v2
	v_mov_b32_e32 v68, v2
	v_mov_b32_e32 v69, v2
	v_mov_b32_e32 v70, v2
	v_mov_b32_e32 v71, v2
	v_mov_b32_e32 v72, v2
	v_mov_b32_e32 v73, v2
	v_mov_b32_e32 v82, v2
	v_mov_b32_e32 v83, v2
	v_mov_b32_e32 v84, v2
	v_mov_b32_e32 v85, v2
	v_mov_b32_e32 v86, v2
	v_mov_b32_e32 v87, v2
	v_mov_b32_e32 v88, v2
	v_mov_b32_e32 v89, v2
	v_mov_b32_e32 v98, v2
	v_mov_b32_e32 v99, v2
	v_mov_b32_e32 v100, v2
	v_mov_b32_e32 v101, v2
	v_mov_b32_e32 v102, v2
	v_mov_b32_e32 v103, v2
	v_mov_b32_e32 v104, v2
	v_mov_b32_e32 v105, v2
	v_mov_b32_e32 v114, v2
	v_mov_b32_e32 v115, v2
	v_mov_b32_e32 v116, v2
	v_mov_b32_e32 v117, v2
	v_mov_b32_e32 v118, v2
	v_mov_b32_e32 v119, v2
	v_mov_b32_e32 v120, v2
	v_mov_b32_e32 v121, v2
	v_mov_b32_e32 v74, v2
	v_mov_b32_e32 v75, v2
	v_mov_b32_e32 v76, v2
	v_mov_b32_e32 v77, v2
	v_mov_b32_e32 v78, v2
	v_mov_b32_e32 v79, v2
	v_mov_b32_e32 v80, v2
	v_mov_b32_e32 v81, v2
	v_mov_b32_e32 v90, v2
	v_mov_b32_e32 v91, v2
	v_mov_b32_e32 v92, v2
	v_mov_b32_e32 v93, v2
	v_mov_b32_e32 v94, v2
	v_mov_b32_e32 v95, v2
	v_mov_b32_e32 v96, v2
	v_mov_b32_e32 v97, v2
	v_mov_b32_e32 v106, v2
	v_mov_b32_e32 v107, v2
	v_mov_b32_e32 v108, v2
	v_mov_b32_e32 v109, v2
	v_mov_b32_e32 v110, v2
	v_mov_b32_e32 v111, v2
	v_mov_b32_e32 v112, v2
	v_mov_b32_e32 v113, v2
	v_mov_b32_e32 v122, v2
	v_mov_b32_e32 v123, v2
	v_mov_b32_e32 v124, v2
	v_mov_b32_e32 v125, v2
	v_mov_b32_e32 v126, v2
	v_mov_b32_e32 v127, v2
	v_mov_b32_e32 v128, v2
	v_mov_b32_e32 v129, v2
	v_readfirstlane_b32 s98, v219
	s_nop 1
	s_bitcmp1_b32 s98, 8
	s_cbranch_scc0 .Lresync_y_825
	s_barrier
.Lresync_y_825:
.LBB0_825:
	s_add_i32 s86, s68, 2
	s_add_u32 s70, s4, 0x80
	s_addc_u32 s69, s5, 0
	s_add_i32 s87, 0, 0x10000
	v_add_u32_e32 v144, s87, v145
	ds_read_b128 v[152:155], v144
	ds_read_b128 v[156:159], v144 offset:1024
	ds_read_b128 v[160:163], v144 offset:2048
	ds_read_b128 v[164:167], v144 offset:3072
	s_cmp_eq_u32 s77, s68
	s_cselect_b32 s68, s59, s70
	s_cselect_b32 s69, s57, s69
	s_cselect_b32 s71, s82, s85
	s_cselect_b32 s70, s83, s84
	v_lshl_add_u64 v[192:193], s[4:5], 0, v[136:137]
	s_add_i32 m0, s33, 0xc000
	ds_read_b128 v[168:171], v151
	ds_read_b128 v[172:175], v151 offset:1024
	ds_read_b128 v[176:179], v151 offset:2048
	ds_read_b128 v[180:183], v151 offset:3072
	ds_read_b128 v[184:187], v151 offset:4096
	ds_read_b128 v[188:191], v151 offset:5120
	ds_read_b128 v[196:199], v151 offset:6144
	ds_read_b128 v[200:203], v151 offset:7168
	global_load_lds_dwordx4 v[192:193], off
	v_lshl_add_u64 v[192:193], s[4:5], 0, v[138:139]
	s_add_i32 m0, s33, 0xe000
	s_nop 0
	global_load_lds_dwordx4 v[192:193], off
	s_add_i32 s88, 0, 0x14000
	v_add_u32_e32 v144, s88, v145
	ds_read_b128 v[204:207], v144
	ds_read_b128 v[208:211], v144 offset:1024
	ds_read_b128 v[212:215], v144 offset:2048
	ds_read_b128 v[234:237], v144 offset:3072
	s_waitcnt vmcnt(8)
	s_waitcnt lgkmcnt(0)
	v_mfma_f32_16x16x32_bf16 v[126:129], v[152:155], v[168:171], v[126:129]
	v_mfma_f32_16x16x32_bf16 v[122:125], v[160:163], v[168:171], v[122:125]
	v_mfma_f32_16x16x32_bf16 v[110:113], v[152:155], v[176:179], v[110:113]
	v_mfma_f32_16x16x32_bf16 v[106:109], v[160:163], v[176:179], v[106:109]
	s_barrier
; #define PG8_STAGE(bufoff, gbase, voff) do { _Pragma("unroll") for (int _i = 0; _i < 2; ++_i) \
;         __builtin_amdgcn_global_load_lds((const unsigned*)((const char*)(gbase) + (voff)[_i]), (LAS unsigned*)(lds + (bufoff) + ldsw + _i * 8192), 16, 0, 0); } while (0)
; #define PG8_LDA(dst, b, h) do { _Pragma("unroll") for (int m = 0; m < 4; ++m) _Pragma("unroll") for (int k = 0; k < 2; ++k) dst[m][k] = *(const LAS bf16x8*)(lds + PG8_SA(b, h) + aoff + m * 2048 + k * 1024); } while (0)
; #define PG8_LDB(dst, b, h) do { _Pragma("unroll") for (int n = 0; n < 2; ++n) _Pragma("unroll") for (int k = 0; k < 2; ++k) dst[n][k] = *(const LAS bf16x8*)(lds + PG8_SB(b, h) + boff + n * 2048 + k * 1024); } while (0)
; #define PG8_MMA(ai, bj, At, Bt) do { __builtin_amdgcn_s_setprio(1); _Pragma("unroll") for (int m = 0; m < 4; ++m) _Pragma("unroll") for (int n = 0; n < 2; ++n) _Pragma("unroll") for (int k = 0; k < 2; ++k) \
;         acc[ai][bj][m][n] = __builtin_amdgcn_mfma_f32_16x16x32_bf16(Bt[n][k], At[m][k], acc[ai][bj][m][n], 0, 0, 0); __builtin_amdgcn_s_setprio(0); } while (0)
; #define PG8_WAIT_V(n) asm volatile("s_waitcnt vmcnt(" #n ")" ::: "memory")
; #define PG8_WAIT_L(n) asm volatile("s_waitcnt lgkmcnt(" #n ")" ::: "memory")
; #define PG8_BAR __builtin_amdgcn_s_barrier()
; #define PG8_SCHED __builtin_amdgcn_sched_barrier(0)
; template <class Epi>
; __device__ __forceinline__ void gemm_phase(LAS unsigned char* lds, const Gemm g, const Sched& S, const Epi& E) {
;     ...
;             PG8_WAIT_L(8); PG8_BAR; PG8_WAIT_L(0); PG8_MMA(0, 0, At, B0); PG8_BAR; PG8_SCHED;
;             PG8_LDB(B1, 0, 1); PG8_STAGE(PG8_SB(0, 0), b2, voffB);
;             PG8_BAR; PG8_WAIT_L(0); PG8_MMA(0, 1, At, B1); PG8_BAR;
;             PG8_LDA(At, 0, 1); PG8_STAGE(PG8_SA(0, 0), a2, voffA);
;             PG8_BAR; PG8_WAIT_L(0); PG8_MMA(1, 0, At, B0); PG8_BAR; PG8_SCHED;
;             PG8_STAGE(PG8_SB(0, 1), b2 + hstepB, voffB);
;             PG8_WAIT_V(6); PG8_BAR; PG8_MMA(1, 1, At, B1); PG8_BAR;
	s_setprio 1
	v_mfma_f32_16x16x32_bf16 v[94:97], v[152:155], v[184:187], v[94:97]
	v_mfma_f32_16x16x32_bf16 v[90:93], v[160:163], v[184:187], v[90:93]
	v_mfma_f32_16x16x32_bf16 v[78:81], v[152:155], v[196:199], v[78:81]
	v_mfma_f32_16x16x32_bf16 v[74:77], v[160:163], v[196:199], v[74:77]
	v_mfma_f32_16x16x32_bf16 v[126:129], v[156:159], v[172:175], v[126:129]
	v_mfma_f32_16x16x32_bf16 v[122:125], v[164:167], v[172:175], v[122:125]
	v_mfma_f32_16x16x32_bf16 v[110:113], v[156:159], v[180:183], v[110:113]
	v_mfma_f32_16x16x32_bf16 v[106:109], v[164:167], v[180:183], v[106:109]
	v_mfma_f32_16x16x32_bf16 v[94:97], v[156:159], v[188:191], v[94:97]
	v_mfma_f32_16x16x32_bf16 v[90:93], v[164:167], v[188:191], v[90:93]
	v_mfma_f32_16x16x32_bf16 v[78:81], v[156:159], v[200:203], v[78:81]
	v_mfma_f32_16x16x32_bf16 v[74:77], v[164:167], v[200:203], v[74:77]
	v_mfma_f32_16x16x32_bf16 v[118:121], v[204:207], v[168:171], v[118:121]
	v_mfma_f32_16x16x32_bf16 v[114:117], v[212:215], v[168:171], v[114:117]
	v_mfma_f32_16x16x32_bf16 v[102:105], v[204:207], v[176:179], v[102:105]
	v_mfma_f32_16x16x32_bf16 v[98:101], v[212:215], v[176:179], v[98:101]
	v_mfma_f32_16x16x32_bf16 v[86:89], v[204:207], v[184:187], v[86:89]
	v_mfma_f32_16x16x32_bf16 v[82:85], v[212:215], v[184:187], v[82:85]
	v_mfma_f32_16x16x32_bf16 v[70:73], v[204:207], v[196:199], v[70:73]
	v_mfma_f32_16x16x32_bf16 v[66:69], v[212:215], v[196:199], v[66:69]
	v_mfma_f32_16x16x32_bf16 v[118:121], v[208:211], v[172:175], v[118:121]
	v_mfma_f32_16x16x32_bf16 v[114:117], v[234:237], v[172:175], v[114:117]
	v_mfma_f32_16x16x32_bf16 v[102:105], v[208:211], v[180:183], v[102:105]
	v_mfma_f32_16x16x32_bf16 v[98:101], v[234:237], v[180:183], v[98:101]
	v_mfma_f32_16x16x32_bf16 v[86:89], v[208:211], v[188:191], v[86:89]
	v_mfma_f32_16x16x32_bf16 v[82:85], v[234:237], v[188:191], v[82:85]
	v_mfma_f32_16x16x32_bf16 v[70:73], v[208:211], v[200:203], v[70:73]
	v_mfma_f32_16x16x32_bf16 v[66:69], v[234:237], v[200:203], v[66:69]
	s_setprio 0
	s_barrier
	s_add_i32 s87, s87, s51
	v_lshl_add_u64 v[192:193], s[70:71], 0, v[0:1]
	s_mov_b32 m0, s87
	s_nop 0
	global_load_lds_dwordx4 v[192:193], off
	v_lshl_add_u64 v[216:217], s[70:71], 0, v[134:135]
	s_add_i32 m0, s87, 0x2000
	s_nop 0
	global_load_lds_dwordx4 v[216:217], off
	s_mov_b32 m0, s33
	v_lshl_add_u64 v[222:223], s[68:69], 0, v[130:131]
	ds_read_b128 v[168:171], v151 offset:16384
	ds_read_b128 v[172:175], v151 offset:17408
	ds_read_b128 v[176:179], v151 offset:18432
	ds_read_b128 v[180:183], v151 offset:19456
	ds_read_b128 v[184:187], v151 offset:20480
	ds_read_b128 v[188:191], v151 offset:21504
	ds_read_b128 v[196:199], v151 offset:22528
	ds_read_b128 v[200:203], v151 offset:23552
	global_load_lds_dwordx4 v[222:223], off
	v_lshl_add_u64 v[224:225], s[68:69], 0, v[132:133]
	s_mov_b32 m0, s48
	s_nop 0
	global_load_lds_dwordx4 v[224:225], off
	s_add_u32 s70, s70, s14
	s_addc_u32 s71, s71, s15
	s_add_i32 s87, s88, s51
	v_lshl_add_u64 v[226:227], s[70:71], 0, v[0:1]
	s_mov_b32 m0, s87
	v_lshl_add_u64 v[228:229], s[70:71], 0, v[134:135]
	global_load_lds_dwordx4 v[226:227], off
	s_add_i32 m0, s87, 0x2000
	s_nop 0
	global_load_lds_dwordx4 v[228:229], off
	s_waitcnt vmcnt(8)
	s_waitcnt lgkmcnt(0)
	v_mfma_f32_16x16x32_bf16 v[62:65], v[152:155], v[168:171], v[62:65]
	v_mfma_f32_16x16x32_bf16 v[58:61], v[160:163], v[168:171], v[58:61]
	v_mfma_f32_16x16x32_bf16 v[46:49], v[152:155], v[176:179], v[46:49]
	v_mfma_f32_16x16x32_bf16 v[42:45], v[160:163], v[176:179], v[42:45]
	s_barrier
	s_setprio 1
	v_mfma_f32_16x16x32_bf16 v[30:33], v[152:155], v[184:187], v[30:33]
	v_mfma_f32_16x16x32_bf16 v[26:29], v[160:163], v[184:187], v[26:29]
	v_mfma_f32_16x16x32_bf16 v[14:17], v[152:155], v[196:199], v[14:17]
	v_mfma_f32_16x16x32_bf16 v[10:13], v[160:163], v[196:199], v[10:13]
	v_mfma_f32_16x16x32_bf16 v[62:65], v[156:159], v[172:175], v[62:65]
	v_mfma_f32_16x16x32_bf16 v[58:61], v[164:167], v[172:175], v[58:61]
	v_mfma_f32_16x16x32_bf16 v[46:49], v[156:159], v[180:183], v[46:49]
	v_mfma_f32_16x16x32_bf16 v[42:45], v[164:167], v[180:183], v[42:45]
	v_mfma_f32_16x16x32_bf16 v[30:33], v[156:159], v[188:191], v[30:33]
	v_mfma_f32_16x16x32_bf16 v[26:29], v[164:167], v[188:191], v[26:29]
	v_mfma_f32_16x16x32_bf16 v[14:17], v[156:159], v[200:203], v[14:17]
	v_mfma_f32_16x16x32_bf16 v[10:13], v[164:167], v[200:203], v[10:13]
	v_mfma_f32_16x16x32_bf16 v[54:57], v[204:207], v[168:171], v[54:57]
	v_mfma_f32_16x16x32_bf16 v[50:53], v[212:215], v[168:171], v[50:53]
	v_mfma_f32_16x16x32_bf16 v[38:41], v[204:207], v[176:179], v[38:41]
	v_mfma_f32_16x16x32_bf16 v[34:37], v[212:215], v[176:179], v[34:37]
	v_mfma_f32_16x16x32_bf16 v[22:25], v[204:207], v[184:187], v[22:25]
	v_mfma_f32_16x16x32_bf16 v[18:21], v[212:215], v[184:187], v[18:21]
	v_mfma_f32_16x16x32_bf16 v[6:9], v[204:207], v[196:199], v[6:9]
	v_mfma_f32_16x16x32_bf16 v[2:5], v[212:215], v[196:199], v[2:5]
	v_mfma_f32_16x16x32_bf16 v[54:57], v[208:211], v[172:175], v[54:57]
	v_mfma_f32_16x16x32_bf16 v[50:53], v[234:237], v[172:175], v[50:53]
	v_mfma_f32_16x16x32_bf16 v[38:41], v[208:211], v[180:183], v[38:41]
	v_mfma_f32_16x16x32_bf16 v[34:37], v[234:237], v[180:183], v[34:37]
	v_mfma_f32_16x16x32_bf16 v[22:25], v[208:211], v[188:191], v[22:25]
	v_mfma_f32_16x16x32_bf16 v[18:21], v[234:237], v[188:191], v[18:21]
	v_mfma_f32_16x16x32_bf16 v[6:9], v[208:211], v[200:203], v[6:9]
	v_mfma_f32_16x16x32_bf16 v[2:5], v[234:237], v[200:203], v[2:5]
	s_setprio 0
	s_barrier
; #define PG8_STAGE(bufoff, gbase, voff) do { _Pragma("unroll") for (int _i = 0; _i < 2; ++_i) \
;         __builtin_amdgcn_global_load_lds((const unsigned*)((const char*)(gbase) + (voff)[_i]), (LAS unsigned*)(lds + (bufoff) + ldsw + _i * 8192), 16, 0, 0); } while (0)
; #define PG8_LDA(dst, b, h) do { _Pragma("unroll") for (int m = 0; m < 4; ++m) _Pragma("unroll") for (int k = 0; k < 2; ++k) dst[m][k] = *(const LAS bf16x8*)(lds + PG8_SA(b, h) + aoff + m * 2048 + k * 1024); } while (0)
; #define PG8_LDB(dst, b, h) do { _Pragma("unroll") for (int n = 0; n < 2; ++n) _Pragma("unroll") for (int k = 0; k < 2; ++k) dst[n][k] = *(const LAS bf16x8*)(lds + PG8_SB(b, h) + boff + n * 2048 + k * 1024); } while (0)
; #define PG8_MMA(ai, bj, At, Bt) do { __builtin_amdgcn_s_setprio(1); _Pragma("unroll") for (int m = 0; m < 4; ++m) _Pragma("unroll") for (int n = 0; n < 2; ++n) _Pragma("unroll") for (int k = 0; k < 2; ++k) \
;         acc[ai][bj][m][n] = __builtin_amdgcn_mfma_f32_16x16x32_bf16(Bt[n][k], At[m][k], acc[ai][bj][m][n], 0, 0, 0); __builtin_amdgcn_s_setprio(0); } while (0)
; #define PG8_WAIT_L(n) asm volatile("s_waitcnt lgkmcnt(" #n ")" ::: "memory")
; #define PG8_BAR __builtin_amdgcn_s_barrier()
; #define PG8_SCHED __builtin_amdgcn_sched_barrier(0)
; template <class Epi>
; __device__ __forceinline__ void gemm_phase(LAS unsigned char* lds, const Gemm g, const Sched& S, const Epi& E) {
;     ...
;             PG8_LDB(B0, 1, 0); PG8_SCHED; PG8_LDA(At, 1, 0); PG8_STAGE(PG8_SA(0, 1), a2 + hstepA, voffA);
;             PG8_WAIT_L(8); PG8_BAR; PG8_WAIT_L(0); PG8_MMA(0, 0, At, B0); PG8_BAR; PG8_SCHED;
;             PG8_LDB(B1, 1, 1); PG8_STAGE(PG8_SB(1, 0), b3, voffB);
;             PG8_BAR; PG8_WAIT_L(0); PG8_MMA(0, 1, At, B1); PG8_BAR;
;             PG8_LDA(At, 1, 1); PG8_STAGE(PG8_SA(1, 0), a3, voffA);
;             PG8_BAR; PG8_WAIT_L(0); PG8_MMA(1, 0, At, B0); PG8_BAR; PG8_SCHED;
;             PG8_STAGE(PG8_SB(1, 1), b3 + hstepB, voffB);
	s_add_i32 s70, 0, 0x18000
	v_add_u32_e32 v144, s70, v145
	ds_read_b128 v[152:155], v144
	ds_read_b128 v[156:159], v144 offset:1024
	ds_read_b128 v[160:163], v144 offset:2048
	ds_read_b128 v[164:167], v144 offset:3072
	s_add_u32 s68, s68, s6
	s_addc_u32 s69, s69, s7
	s_mov_b32 m0, s58
	v_lshl_add_u64 v[204:205], s[68:69], 0, v[130:131]
	ds_read_b128 v[168:171], v151 offset:32768
	ds_read_b128 v[172:175], v151 offset:33792
	ds_read_b128 v[176:179], v151 offset:34816
	ds_read_b128 v[180:183], v151 offset:35840
	ds_read_b128 v[184:187], v151 offset:36864
	ds_read_b128 v[188:191], v151 offset:37888
	ds_read_b128 v[196:199], v151 offset:38912
	ds_read_b128 v[200:203], v151 offset:39936
	global_load_lds_dwordx4 v[204:205], off
	v_lshl_add_u64 v[204:205], s[68:69], 0, v[132:133]
	s_mov_b32 m0, s72
	s_nop 0
	global_load_lds_dwordx4 v[204:205], off
	s_add_i32 s68, 0, 0x1c000
	v_add_u32_e32 v144, s68, v145
	ds_read_b128 v[204:207], v144
	ds_read_b128 v[208:211], v144 offset:1024
	ds_read_b128 v[212:215], v144 offset:2048
	ds_read_b128 v[234:237], v144 offset:3072
	s_waitcnt vmcnt(8)
	s_waitcnt lgkmcnt(0)
	v_mfma_f32_16x16x32_bf16 v[126:129], v[152:155], v[168:171], v[126:129]
	v_mfma_f32_16x16x32_bf16 v[122:125], v[160:163], v[168:171], v[122:125]
	v_mfma_f32_16x16x32_bf16 v[110:113], v[152:155], v[176:179], v[110:113]
	v_mfma_f32_16x16x32_bf16 v[106:109], v[160:163], v[176:179], v[106:109]
	s_barrier
	s_setprio 1
	v_mfma_f32_16x16x32_bf16 v[94:97], v[152:155], v[184:187], v[94:97]
	v_mfma_f32_16x16x32_bf16 v[90:93], v[160:163], v[184:187], v[90:93]
	v_mfma_f32_16x16x32_bf16 v[78:81], v[152:155], v[196:199], v[78:81]
	v_mfma_f32_16x16x32_bf16 v[74:77], v[160:163], v[196:199], v[74:77]
	v_mfma_f32_16x16x32_bf16 v[126:129], v[156:159], v[172:175], v[126:129]
	v_mfma_f32_16x16x32_bf16 v[122:125], v[164:167], v[172:175], v[122:125]
	v_mfma_f32_16x16x32_bf16 v[110:113], v[156:159], v[180:183], v[110:113]
	v_mfma_f32_16x16x32_bf16 v[106:109], v[164:167], v[180:183], v[106:109]
	v_mfma_f32_16x16x32_bf16 v[94:97], v[156:159], v[188:191], v[94:97]
	v_mfma_f32_16x16x32_bf16 v[90:93], v[164:167], v[188:191], v[90:93]
	v_mfma_f32_16x16x32_bf16 v[78:81], v[156:159], v[200:203], v[78:81]
	v_mfma_f32_16x16x32_bf16 v[74:77], v[164:167], v[200:203], v[74:77]
	v_mfma_f32_16x16x32_bf16 v[118:121], v[204:207], v[168:171], v[118:121]
	v_mfma_f32_16x16x32_bf16 v[114:117], v[212:215], v[168:171], v[114:117]
	v_mfma_f32_16x16x32_bf16 v[102:105], v[204:207], v[176:179], v[102:105]
	v_mfma_f32_16x16x32_bf16 v[98:101], v[212:215], v[176:179], v[98:101]
	v_mfma_f32_16x16x32_bf16 v[86:89], v[204:207], v[184:187], v[86:89]
	v_mfma_f32_16x16x32_bf16 v[82:85], v[212:215], v[184:187], v[82:85]
	v_mfma_f32_16x16x32_bf16 v[70:73], v[204:207], v[196:199], v[70:73]
	v_mfma_f32_16x16x32_bf16 v[66:69], v[212:215], v[196:199], v[66:69]
	v_mfma_f32_16x16x32_bf16 v[118:121], v[208:211], v[172:175], v[118:121]
	v_mfma_f32_16x16x32_bf16 v[114:117], v[234:237], v[172:175], v[114:117]
	v_mfma_f32_16x16x32_bf16 v[102:105], v[208:211], v[180:183], v[102:105]
	v_mfma_f32_16x16x32_bf16 v[98:101], v[234:237], v[180:183], v[98:101]
	v_mfma_f32_16x16x32_bf16 v[86:89], v[208:211], v[188:191], v[86:89]
	v_mfma_f32_16x16x32_bf16 v[82:85], v[234:237], v[188:191], v[82:85]
	v_mfma_f32_16x16x32_bf16 v[70:73], v[208:211], v[200:203], v[70:73]
	v_mfma_f32_16x16x32_bf16 v[66:69], v[234:237], v[200:203], v[66:69]
	s_setprio 0
	s_barrier
	s_add_i32 s69, s70, s51
	v_lshl_add_u64 v[192:193], v[192:193], 0, s[60:61]
	s_mov_b32 m0, s69
	s_nop 0
	global_load_lds_dwordx4 v[192:193], off
	v_lshl_add_u64 v[192:193], v[216:217], 0, s[60:61]
	s_add_i32 m0, s69, 0x2000
	s_nop 0
	global_load_lds_dwordx4 v[192:193], off
	s_mov_b32 m0, s75
	v_lshl_add_u64 v[192:193], v[222:223], 0, s[60:61]
	ds_read_b128 v[168:171], v151 offset:49152
	ds_read_b128 v[172:175], v151 offset:50176
	ds_read_b128 v[176:179], v151 offset:51200
	ds_read_b128 v[180:183], v151 offset:52224
	ds_read_b128 v[184:187], v151 offset:53248
	ds_read_b128 v[188:191], v151 offset:54272
	ds_read_b128 v[196:199], v151 offset:55296
	ds_read_b128 v[200:203], v151 offset:56320
	global_load_lds_dwordx4 v[192:193], off
	v_lshl_add_u64 v[192:193], v[224:225], 0, s[60:61]
	s_mov_b32 m0, s76
	s_nop 0
	global_load_lds_dwordx4 v[192:193], off
	s_add_i32 s68, s68, s51
	v_lshl_add_u64 v[192:193], v[226:227], 0, s[60:61]
	s_mov_b32 m0, s68
	s_nop 0
	global_load_lds_dwordx4 v[192:193], off
	v_lshl_add_u64 v[192:193], v[228:229], 0, s[60:61]
	s_add_i32 m0, s68, 0x2000
	s_nop 0
	global_load_lds_dwordx4 v[192:193], off
	s_waitcnt vmcnt(8)
	s_waitcnt lgkmcnt(0)
	v_mfma_f32_16x16x32_bf16 v[62:65], v[152:155], v[168:171], v[62:65]
	v_mfma_f32_16x16x32_bf16 v[58:61], v[160:163], v[168:171], v[58:61]
	v_mfma_f32_16x16x32_bf16 v[46:49], v[152:155], v[176:179], v[46:49]
	v_mfma_f32_16x16x32_bf16 v[42:45], v[160:163], v[176:179], v[42:45]
	s_barrier
; __device__ __forceinline__ float silu_f(float x) { return x * __builtin_amdgcn_rcpf(1.f + __builtin_amdgcn_exp2f(-LOG2E * x)); }
; __device__ __forceinline__ float pre_get(const Pre& p, int ai, int m, int fr) { return __shfl(p.v[ai], m * 16 + fr); }
; __device__ __forceinline__ float rstd_pre(const float* ss, float v) { return ss ? rsqrtf(v * (1.0f / 2048.0f) + 1e-6f) : 1.0f; }
; #define PG8_STAGE(bufoff, gbase, voff) do { _Pragma("unroll") for (int _i = 0; _i < 2; ++_i) \
;         __builtin_amdgcn_global_load_lds((const unsigned*)((const char*)(gbase) + (voff)[_i]), (LAS unsigned*)(lds + (bufoff) + ldsw + _i * 8192), 16, 0, 0); } while (0)
; #define PG8_MMA(ai, bj, At, Bt) do { __builtin_amdgcn_s_setprio(1); _Pragma("unroll") for (int m = 0; m < 4; ++m) _Pragma("unroll") for (int n = 0; n < 2; ++n) _Pragma("unroll") for (int k = 0; k < 2; ++k) \
;         acc[ai][bj][m][n] = __builtin_amdgcn_mfma_f32_16x16x32_bf16(Bt[n][k], At[m][k], acc[ai][bj][m][n], 0, 0, 0); __builtin_amdgcn_s_setprio(0); } while (0)
; #define PG8_WAIT_V(n) asm volatile("s_waitcnt vmcnt(" #n ")" ::: "memory")
; #define PG8_BAR __builtin_amdgcn_s_barrier()
; template <class Epi>
; __device__ __forceinline__ void gemm_phase(LAS unsigned char* lds, const Gemm g, const Sched& S, const Epi& E) {
;     ...
;             PG8_STAGE(PG8_SB(1, 1), b3 + hstepB, voffB);
;             PG8_WAIT_V(6); PG8_BAR; PG8_MMA(1, 1, At, B1); PG8_BAR;
;         }
;         E(acc, cur, wr, wc, fr, fq, pre);
;         if (!has_next) break;
;     __device__ __forceinline__ void operator()(const Acc& acc, const Unit& u, int wr, int wc, int fr, int fq, const Pre& pre) const {
;     ...
; #pragma unroll
;         for (int ai = 0; ai < 2; ++ai)
; #pragma unroll
;             for (int m = 0; m < 4; ++m) rsq[ai][m] = rstd_pre(ss, pre_get(pre, ai, m, fr));
; #pragma unroll
;         for (int ai = 0; ai < 2; ++ai)
; #pragma unroll
;             for (int m = 0; m < 4; ++m) {
;                 f32x4 v0, v1; const float rs = rsq[ai][m];
; #pragma unroll
;                 for (int e = 0; e < 4; ++e) { v0[e] = silu_f(acc[ai][0][m][0][e] * rs) * (acc[ai][1][m][0][e] * rs); v1[e] = silu_f(acc[ai][0][m][1][e] * rs) * (acc[ai][1][m][1][e] * rs); }
	s_setprio 1
	v_mfma_f32_16x16x32_bf16 v[30:33], v[152:155], v[184:187], v[30:33]
	v_mfma_f32_16x16x32_bf16 v[26:29], v[160:163], v[184:187], v[26:29]
	v_mfma_f32_16x16x32_bf16 v[14:17], v[152:155], v[196:199], v[14:17]
	v_mfma_f32_16x16x32_bf16 v[10:13], v[160:163], v[196:199], v[10:13]
	v_mfma_f32_16x16x32_bf16 v[62:65], v[156:159], v[172:175], v[62:65]
	v_mfma_f32_16x16x32_bf16 v[58:61], v[164:167], v[172:175], v[58:61]
	v_mfma_f32_16x16x32_bf16 v[46:49], v[156:159], v[180:183], v[46:49]
	v_mfma_f32_16x16x32_bf16 v[42:45], v[164:167], v[180:183], v[42:45]
	v_mfma_f32_16x16x32_bf16 v[30:33], v[156:159], v[188:191], v[30:33]
	v_mfma_f32_16x16x32_bf16 v[26:29], v[164:167], v[188:191], v[26:29]
	v_mfma_f32_16x16x32_bf16 v[14:17], v[156:159], v[200:203], v[14:17]
	v_mfma_f32_16x16x32_bf16 v[10:13], v[164:167], v[200:203], v[10:13]
	v_mfma_f32_16x16x32_bf16 v[54:57], v[204:207], v[168:171], v[54:57]
	v_mfma_f32_16x16x32_bf16 v[50:53], v[212:215], v[168:171], v[50:53]
	v_mfma_f32_16x16x32_bf16 v[38:41], v[204:207], v[176:179], v[38:41]
	v_mfma_f32_16x16x32_bf16 v[34:37], v[212:215], v[176:179], v[34:37]
	v_mfma_f32_16x16x32_bf16 v[22:25], v[204:207], v[184:187], v[22:25]
	v_mfma_f32_16x16x32_bf16 v[18:21], v[212:215], v[184:187], v[18:21]
	v_mfma_f32_16x16x32_bf16 v[6:9], v[204:207], v[196:199], v[6:9]
	v_mfma_f32_16x16x32_bf16 v[2:5], v[212:215], v[196:199], v[2:5]
	v_mfma_f32_16x16x32_bf16 v[54:57], v[208:211], v[172:175], v[54:57]
	v_mfma_f32_16x16x32_bf16 v[50:53], v[234:237], v[172:175], v[50:53]
	v_mfma_f32_16x16x32_bf16 v[38:41], v[208:211], v[180:183], v[38:41]
	v_mfma_f32_16x16x32_bf16 v[34:37], v[234:237], v[180:183], v[34:37]
	v_mfma_f32_16x16x32_bf16 v[22:25], v[208:211], v[188:191], v[22:25]
	v_mfma_f32_16x16x32_bf16 v[18:21], v[234:237], v[188:191], v[18:21]
	v_mfma_f32_16x16x32_bf16 v[6:9], v[208:211], v[200:203], v[6:9]
	v_mfma_f32_16x16x32_bf16 v[2:5], v[234:237], v[200:203], v[2:5]
	s_setprio 0
	s_add_u32 s4, s4, 0x100
	s_addc_u32 s5, s5, 0
	s_add_u32 s84, s84, 0x100
	s_addc_u32 s85, s85, 0
	s_cmp_ge_u32 s86, s73
	s_mov_b32 s68, s86
	s_barrier
	s_cbranch_scc0 .LBB0_825
	v_readfirstlane_b32 s98, v219
	s_nop 1
	s_bitcmp1_b32 s98, 8
	s_cbranch_scc1 .Lresync_x_825
	s_barrier
.Lresync_x_825:
	v_and_or_b32 v144, v220, 64, v141
	v_lshlrev_b32_e32 v160, 2, v144
	ds_bpermute_b32 v155, v160, v142
	ds_bpermute_b32 v154, v160, v142 offset:64
	s_mov_b32 s4, 0x358637bd
	v_mov_b64_e32 v[156:157], s[4:5]
	s_mov_b32 s8, 0x3a000000
	v_lshl_add_u32 v153, s81, 8, v143
	s_waitcnt lgkmcnt(0)
	v_pk_fma_f32 v[158:159], v[154:155], s[8:9], v[156:157] op_sel_hi:[1,0,0]
	s_mov_b32 s81, s80
	v_mul_f32_e32 v144, 0x4b800000, v159
	v_cmp_gt_f32_e64 s[4:5], s97, v159
	v_cmp_gt_f32_e32 vcc, s97, v158
	s_mov_b64 s[68:69], s[66:67]
	v_cndmask_b32_e64 v144, v159, v144, s[4:5]
	v_rsq_f32_e32 v144, v144
	ds_bpermute_b32 v159, v160, v142 offset:128
	v_mul_f32_e32 v146, 0x45800000, v144
	v_cndmask_b32_e64 v144, v144, v146, s[4:5]
	v_cndmask_b32_e64 v154, v144, 1.0, s[34:35]
	v_mul_f32_e32 v144, 0x4b800000, v158
	v_cndmask_b32_e32 v144, v158, v144, vcc
	ds_bpermute_b32 v158, v160, v142 offset:192
	v_rsq_f32_e32 v144, v144
	s_waitcnt lgkmcnt(0)
	v_pk_fma_f32 v[158:159], v[158:159], s[8:9], v[156:157] op_sel_hi:[1,0,0]
	s_nop 0
	v_mul_f32_e32 v142, 0x4b800000, v159
	v_cmp_gt_f32_e64 s[4:5], s97, v159
	v_mul_f32_e32 v146, 0x45800000, v144
	v_cndmask_b32_e32 v144, v144, v146, vcc
	v_cndmask_b32_e64 v142, v159, v142, s[4:5]
	v_rsq_f32_e32 v142, v142
	v_cndmask_b32_e64 v152, v144, 1.0, s[34:35]
	v_cmp_gt_f32_e32 vcc, s97, v158
	ds_bpermute_b32 v159, v160, v140
	v_mul_f32_e32 v144, 0x45800000, v142
	v_cndmask_b32_e64 v142, v142, v144, s[4:5]
	v_cndmask_b32_e64 v150, v142, 1.0, s[34:35]
	v_mul_f32_e32 v142, 0x4b800000, v158
	v_cndmask_b32_e32 v142, v158, v142, vcc
	v_rsq_f32_e32 v142, v142
	ds_bpermute_b32 v158, v160, v140 offset:64
	v_pk_mul_f32 v[110:111], v[110:111], v[152:153] op_sel_hi:[1,0]
	v_pk_mul_f32 v[102:103], v[102:103], v[152:153] op_sel_hi:[1,0]
	v_mul_f32_e32 v144, 0x45800000, v142
	v_cndmask_b32_e32 v142, v142, v144, vcc
	s_waitcnt lgkmcnt(0)
	v_pk_fma_f32 v[158:159], v[158:159], s[8:9], v[156:157] op_sel_hi:[1,0,0]
	v_cndmask_b32_e64 v148, v142, 1.0, s[34:35]
	v_mul_f32_e32 v142, 0x4b800000, v159
	v_cmp_gt_f32_e64 s[4:5], s97, v159
	v_cmp_gt_f32_e32 vcc, s97, v158
	v_pk_mul_f32 v[106:107], v[106:107], v[152:153] op_sel_hi:[1,0]
	v_cndmask_b32_e64 v142, v159, v142, s[4:5]
	v_rsq_f32_e32 v142, v142
	ds_bpermute_b32 v159, v160, v140 offset:128
	v_pk_mul_f32 v[98:99], v[98:99], v[152:153] op_sel_hi:[1,0]
	v_pk_mul_f32 v[104:105], v[104:105], v[152:153] op_sel_hi:[1,0]
	v_mul_f32_e32 v144, 0x45800000, v142
	v_cndmask_b32_e64 v142, v142, v144, s[4:5]
	v_cndmask_b32_e64 v146, v142, 1.0, s[34:35]
	v_mul_f32_e32 v142, 0x4b800000, v158
	v_cndmask_b32_e32 v142, v158, v142, vcc
	ds_bpermute_b32 v158, v160, v140 offset:192
	v_rsq_f32_e32 v142, v142
	v_pk_mul_f32 v[100:101], v[100:101], v[152:153] op_sel_hi:[1,0]
	v_pk_mul_f32 v[94:95], v[94:95], v[150:151] op_sel_hi:[1,0]
	v_pk_mul_f32 v[86:87], v[86:87], v[150:151] op_sel_hi:[1,0]
	s_waitcnt lgkmcnt(0)
; __device__ __forceinline__ float silu_f(float x) { return x * __builtin_amdgcn_rcpf(1.f + __builtin_amdgcn_exp2f(-LOG2E * x)); }
; __device__ __forceinline__ u32x4 pk8(const f32x4 a, const f32x4 b) { u32x4 w; w.x = pk2(a[0], a[1]); w.y = pk2(a[2], a[3]); w.z = pk2(b[0], b[1]); w.w = pk2(b[2], b[3]); return w; }
; __device__ __forceinline__ float pre_get(const Pre& p, int ai, int m, int fr) { return __shfl(p.v[ai], m * 16 + fr); }
; __device__ __forceinline__ float rstd_pre(const float* ss, float v) { return ss ? rsqrtf(v * (1.0f / 2048.0f) + 1e-6f) : 1.0f; }
;     __device__ __forceinline__ void operator()(const Acc& acc, const Unit& u, int wr, int wc, int fr, int fq, const Pre& pre) const {
;     ...
; #pragma unroll
;         for (int ai = 0; ai < 2; ++ai)
; #pragma unroll
;             for (int m = 0; m < 4; ++m) rsq[ai][m] = rstd_pre(ss, pre_get(pre, ai, m, fr));
; #pragma unroll
;         for (int ai = 0; ai < 2; ++ai)
; #pragma unroll
;             for (int m = 0; m < 4; ++m) {
;                 f32x4 v0, v1; const float rs = rsq[ai][m];
; #pragma unroll
;                 for (int e = 0; e < 4; ++e) { v0[e] = silu_f(acc[ai][0][m][0][e] * rs) * (acc[ai][1][m][0][e] * rs); v1[e] = silu_f(acc[ai][0][m][1][e] * rs) * (acc[ai][1][m][1][e] * rs); }
;                 *(u32x4*)(O + (size_t)(row0 + ai * 128 + m * 16) * ldc + col0) = pk8(v0, v1);
;             }
	v_pk_fma_f32 v[156:157], v[158:159], s[8:9], v[156:157] op_sel_hi:[1,0,0]
	v_mul_f32_e32 v144, 0x45800000, v142
	v_mul_f32_e32 v140, 0x4b800000, v157
	v_cmp_gt_f32_e64 s[4:5], s97, v157
	v_cndmask_b32_e32 v142, v142, v144, vcc
	v_cndmask_b32_e64 v144, v142, 1.0, s[34:35]
	v_cndmask_b32_e64 v140, v157, v140, s[4:5]
	v_rsq_f32_e32 v140, v140
	v_cmp_gt_f32_e32 vcc, s97, v156
	v_pk_mul_f32 v[90:91], v[90:91], v[150:151] op_sel_hi:[1,0]
	v_pk_mul_f32 v[82:83], v[82:83], v[150:151] op_sel_hi:[1,0]
	v_mul_f32_e32 v142, 0x45800000, v140
	v_cndmask_b32_e64 v140, v140, v142, s[4:5]
	v_cndmask_b32_e64 v142, v140, 1.0, s[34:35]
	v_mul_f32_e32 v140, 0x4b800000, v156
	v_cndmask_b32_e32 v140, v156, v140, vcc
	v_rsq_f32_e32 v140, v140
	v_lshl_or_b32 v156, s55, 7, v149
	v_ashrrev_i32_e32 v157, 31, v156
	v_pk_mul_f32 v[88:89], v[88:89], v[150:151] op_sel_hi:[1,0]
	v_mul_f32_e32 v155, 0x45800000, v140
	v_pk_mul_f32 v[126:127], v[126:127], v[154:155] op_sel_hi:[1,0]
	v_cndmask_b32_e32 v140, v140, v155, vcc
	v_mul_f32_e32 v155, 0xbfb8aa3b, v126
	v_exp_f32_e32 v155, v155
	v_pk_mul_f32 v[84:85], v[84:85], v[150:151] op_sel_hi:[1,0]
	v_pk_mul_f32 v[78:79], v[78:79], v[148:149] op_sel_hi:[1,0]
	v_pk_mul_f32 v[70:71], v[70:71], v[148:149] op_sel_hi:[1,0]
	v_add_f32_e32 v155, 1.0, v155
	v_rcp_f32_e32 v158, v155
	v_mul_f32_e32 v155, 0xbfb8aa3b, v127
	v_exp_f32_e32 v155, v155
	v_pk_mul_f32 v[74:75], v[74:75], v[148:149] op_sel_hi:[1,0]
	v_pk_mul_f32 v[66:67], v[66:67], v[148:149] op_sel_hi:[1,0]
	v_pk_mul_f32 v[72:73], v[72:73], v[148:149] op_sel_hi:[1,0]
	v_add_f32_e32 v155, 1.0, v155
	v_rcp_f32_e32 v159, v155
	v_pk_mul_f32 v[118:119], v[118:119], v[154:155] op_sel_hi:[1,0]
	v_pk_mul_f32 v[122:123], v[122:123], v[154:155] op_sel_hi:[1,0]
	v_pk_mul_f32 v[114:115], v[114:115], v[154:155] op_sel_hi:[1,0]
	v_pk_mul_f32 v[126:127], v[126:127], v[158:159]
	v_pk_mul_f32 v[120:121], v[120:121], v[154:155] op_sel_hi:[1,0]
	v_pk_mul_f32 v[118:119], v[118:119], v[126:127]
	v_mul_f32_e32 v126, 0xbfb8aa3b, v122
	v_mul_f32_e32 v127, 0xbfb8aa3b, v123
	v_exp_f32_e32 v126, v126
	v_exp_f32_e32 v127, v127
	v_pk_mul_f32 v[116:117], v[116:117], v[154:155] op_sel_hi:[1,0]
	v_cvt_pk_bf16_f32 v118, v118, v119
	v_add_f32_e32 v126, 1.0, v126
	v_add_f32_e32 v127, 1.0, v127
	v_rcp_f32_e32 v126, v126
	v_rcp_f32_e32 v127, v127
	v_pk_mul_f32 v[68:69], v[68:69], v[148:149] op_sel_hi:[1,0]
	v_pk_mul_f32 v[62:63], v[62:63], v[146:147] op_sel_hi:[1,0]
	v_pk_mul_f32 v[54:55], v[54:55], v[146:147] op_sel_hi:[1,0]
	v_pk_mul_f32 v[122:123], v[122:123], v[126:127]
	v_pk_mul_f32 v[58:59], v[58:59], v[146:147] op_sel_hi:[1,0]
	v_pk_mul_f32 v[114:115], v[114:115], v[122:123]
	v_pk_mul_f32 v[122:123], v[128:129], v[154:155] op_sel_hi:[1,0]
	v_pk_mul_f32 v[50:51], v[50:51], v[146:147] op_sel_hi:[1,0]
	v_mul_f32_e32 v126, 0xbfb8aa3b, v122
	v_mul_f32_e32 v127, 0xbfb8aa3b, v123
	v_exp_f32_e32 v126, v126
	v_exp_f32_e32 v127, v127
	v_pk_mul_f32 v[56:57], v[56:57], v[146:147] op_sel_hi:[1,0]
	v_pk_mul_f32 v[52:53], v[52:53], v[146:147] op_sel_hi:[1,0]
	v_add_f32_e32 v126, 1.0, v126
	v_add_f32_e32 v127, 1.0, v127
	v_rcp_f32_e32 v126, v126
	v_rcp_f32_e32 v127, v127
	v_pk_mul_f32 v[46:47], v[46:47], v[144:145] op_sel_hi:[1,0]
	v_pk_mul_f32 v[38:39], v[38:39], v[144:145] op_sel_hi:[1,0]
	v_pk_mul_f32 v[42:43], v[42:43], v[144:145] op_sel_hi:[1,0]
	v_pk_mul_f32 v[122:123], v[122:123], v[126:127]
	v_pk_mul_f32 v[34:35], v[34:35], v[144:145] op_sel_hi:[1,0]
	v_pk_mul_f32 v[120:121], v[120:121], v[122:123]
	v_pk_mul_f32 v[122:123], v[124:125], v[154:155] op_sel_hi:[1,0]
	v_cvt_pk_bf16_f32 v119, v120, v121
	v_mul_f32_e32 v124, 0xbfb8aa3b, v122
	v_mul_f32_e32 v125, 0xbfb8aa3b, v123
	v_exp_f32_e32 v124, v124
	v_exp_f32_e32 v125, v125
	v_cvt_pk_bf16_f32 v120, v114, v115
	v_ashrrev_i32_e32 v114, 31, v153
	v_add_f32_e32 v124, 1.0, v124
	v_add_f32_e32 v125, 1.0, v125
	v_rcp_f32_e32 v124, v124
	v_rcp_f32_e32 v125, v125
	v_pk_mul_f32 v[40:41], v[40:41], v[144:145] op_sel_hi:[1,0]
	v_pk_mul_f32 v[36:37], v[36:37], v[144:145] op_sel_hi:[1,0]
	v_pk_mul_f32 v[30:31], v[30:31], v[142:143] op_sel_hi:[1,0]
	v_pk_mul_f32 v[122:123], v[122:123], v[124:125]
	v_pk_mul_f32 v[22:23], v[22:23], v[142:143] op_sel_hi:[1,0]
	v_pk_mul_f32 v[116:117], v[116:117], v[122:123]
	v_pk_mul_f32 v[26:27], v[26:27], v[142:143] op_sel_hi:[1,0]
	v_cvt_pk_bf16_f32 v121, v116, v117
	v_mul_lo_u32 v116, s12, v114
	v_mul_lo_u32 v117, s13, v153
	v_mad_u64_u32 v[114:115], s[4:5], s12, v153, 0
	v_add3_u32 v115, v115, v116, v117
	v_mul_f32_e32 v117, 0xbfb8aa3b, v110
	v_exp_f32_e32 v117, v117
	v_lshl_add_u64 v[122:123], v[114:115], 1, s[62:63]
	v_lshlrev_b64 v[114:115], 1, v[156:157]
	v_lshl_add_u64 v[122:123], v[122:123], 0, v[114:115]
	v_add_f32_e32 v117, 1.0, v117
	global_store_dwordx4 v[122:123], v[118:121], off
	v_pk_mul_f32 v[18:19], v[18:19], v[142:143] op_sel_hi:[1,0]
	v_pk_mul_f32 v[24:25], v[24:25], v[142:143] op_sel_hi:[1,0]
	v_rcp_f32_e32 v118, v117
	v_mul_f32_e32 v117, 0xbfb8aa3b, v111
	v_exp_f32_e32 v117, v117
	v_pk_mul_f32 v[20:21], v[20:21], v[142:143] op_sel_hi:[1,0]
	v_cndmask_b32_e64 v140, v140, 1.0, s[34:35]
	v_pk_mul_f32 v[14:15], v[14:15], v[140:141] op_sel_hi:[1,0]
	v_add_f32_e32 v117, 1.0, v117
	v_rcp_f32_e32 v119, v117
	v_pk_mul_f32 v[6:7], v[6:7], v[140:141] op_sel_hi:[1,0]
	v_pk_mul_f32 v[10:11], v[10:11], v[140:141] op_sel_hi:[1,0]
	v_pk_mul_f32 v[2:3], v[2:3], v[140:141] op_sel_hi:[1,0]
	v_pk_mul_f32 v[110:111], v[110:111], v[118:119]
	v_pk_mul_f32 v[8:9], v[8:9], v[140:141] op_sel_hi:[1,0]
	v_pk_mul_f32 v[102:103], v[102:103], v[110:111]
	v_mul_f32_e32 v110, 0xbfb8aa3b, v106
	v_mul_f32_e32 v111, 0xbfb8aa3b, v107
	v_exp_f32_e32 v110, v110
; __device__ __forceinline__ float silu_f(float x) { return x * __builtin_amdgcn_rcpf(1.f + __builtin_amdgcn_exp2f(-LOG2E * x)); }
; __device__ __forceinline__ u32x4 pk8(const f32x4 a, const f32x4 b) { u32x4 w; w.x = pk2(a[0], a[1]); w.y = pk2(a[2], a[3]); w.z = pk2(b[0], b[1]); w.w = pk2(b[2], b[3]); return w; }
; __device__ __forceinline__ float pre_get(const Pre& p, int ai, int m, int fr) { return __shfl(p.v[ai], m * 16 + fr); }
; __device__ __forceinline__ float rstd_pre(const float* ss, float v) { return ss ? rsqrtf(v * (1.0f / 2048.0f) + 1e-6f) : 1.0f; }
;     __device__ __forceinline__ void operator()(const Acc& acc, const Unit& u, int wr, int wc, int fr, int fq, const Pre& pre) const {
;     ...
; #pragma unroll
;         for (int ai = 0; ai < 2; ++ai)
; #pragma unroll
;             for (int m = 0; m < 4; ++m) rsq[ai][m] = rstd_pre(ss, pre_get(pre, ai, m, fr));
; #pragma unroll
;         for (int ai = 0; ai < 2; ++ai)
; #pragma unroll
;             for (int m = 0; m < 4; ++m) {
;                 f32x4 v0, v1; const float rs = rsq[ai][m];
; #pragma unroll
;                 for (int e = 0; e < 4; ++e) { v0[e] = silu_f(acc[ai][0][m][0][e] * rs) * (acc[ai][1][m][0][e] * rs); v1[e] = silu_f(acc[ai][0][m][1][e] * rs) * (acc[ai][1][m][1][e] * rs); }
;                 *(u32x4*)(O + (size_t)(row0 + ai * 128 + m * 16) * ldc + col0) = pk8(v0, v1);
;             }
	v_exp_f32_e32 v111, v111
	v_pk_mul_f32 v[4:5], v[4:5], v[140:141] op_sel_hi:[1,0]
	s_and_b64 vcc, exec, s[0:1]
	v_add_f32_e32 v110, 1.0, v110
	v_add_f32_e32 v111, 1.0, v111
	v_rcp_f32_e32 v110, v110
	v_rcp_f32_e32 v111, v111
	s_mov_b32 s55, s79
	v_pk_mul_f32 v[106:107], v[106:107], v[110:111]
	s_nop 0
	v_pk_mul_f32 v[106:107], v[98:99], v[106:107]
	v_pk_mul_f32 v[98:99], v[112:113], v[152:153] op_sel_hi:[1,0]
	s_nop 0
	v_mul_f32_e32 v110, 0xbfb8aa3b, v98
	v_mul_f32_e32 v111, 0xbfb8aa3b, v99
	v_exp_f32_e32 v110, v110
	v_exp_f32_e32 v111, v111
	v_add_f32_e32 v110, 1.0, v110
	v_add_f32_e32 v111, 1.0, v111
	v_rcp_f32_e32 v110, v110
	v_rcp_f32_e32 v111, v111
	s_nop 0
	v_pk_mul_f32 v[98:99], v[98:99], v[110:111]
	s_nop 0
	v_pk_mul_f32 v[104:105], v[104:105], v[98:99]
	v_pk_mul_f32 v[98:99], v[108:109], v[152:153] op_sel_hi:[1,0]
	s_nop 0
	v_mul_f32_e32 v108, 0xbfb8aa3b, v98
	v_mul_f32_e32 v109, 0xbfb8aa3b, v99
	v_exp_f32_e32 v108, v108
	v_exp_f32_e32 v109, v109
	v_add_f32_e32 v108, 1.0, v108
	v_add_f32_e32 v109, 1.0, v109
	v_rcp_f32_e32 v108, v108
	v_rcp_f32_e32 v109, v109
	s_nop 0
	v_pk_mul_f32 v[98:99], v[98:99], v[108:109]
	s_nop 0
	v_pk_mul_f32 v[108:109], v[100:101], v[98:99]
	v_cvt_pk_bf16_f32 v98, v102, v103
	v_or_b32_e32 v102, 16, v153
	v_cvt_pk_bf16_f32 v99, v104, v105
	v_mul_lo_u32 v104, s13, v102
	v_mad_u64_u32 v[102:103], s[4:5], s12, v102, 0
	v_add3_u32 v103, v103, v116, v104
	v_lshl_add_u64 v[102:103], v[102:103], 1, s[62:63]
	v_cvt_pk_bf16_f32 v100, v106, v107
	v_cvt_pk_bf16_f32 v101, v108, v109
	v_lshl_add_u64 v[102:103], v[102:103], 0, v[114:115]
	global_store_dwordx4 v[102:103], v[98:101], off
	s_nop 1
	v_mul_f32_e32 v98, 0xbfb8aa3b, v94
	v_mul_f32_e32 v99, 0xbfb8aa3b, v95
	v_exp_f32_e32 v98, v98
	v_exp_f32_e32 v99, v99
	v_add_f32_e32 v98, 1.0, v98
	v_add_f32_e32 v99, 1.0, v99
	v_rcp_f32_e32 v98, v98
	v_rcp_f32_e32 v99, v99
	s_nop 0
	v_pk_mul_f32 v[94:95], v[94:95], v[98:99]
	s_nop 0
	v_pk_mul_f32 v[86:87], v[86:87], v[94:95]
	v_mul_f32_e32 v94, 0xbfb8aa3b, v90
	v_mul_f32_e32 v95, 0xbfb8aa3b, v91
	v_exp_f32_e32 v94, v94
	v_exp_f32_e32 v95, v95
	v_add_f32_e32 v94, 1.0, v94
	v_add_f32_e32 v95, 1.0, v95
	v_rcp_f32_e32 v94, v94
	v_rcp_f32_e32 v95, v95
	s_nop 0
	v_pk_mul_f32 v[90:91], v[90:91], v[94:95]
	s_nop 0
	v_pk_mul_f32 v[90:91], v[82:83], v[90:91]
	v_pk_mul_f32 v[82:83], v[96:97], v[150:151] op_sel_hi:[1,0]
	s_nop 0
	v_mul_f32_e32 v94, 0xbfb8aa3b, v82
	v_mul_f32_e32 v95, 0xbfb8aa3b, v83
	v_exp_f32_e32 v94, v94
	v_exp_f32_e32 v95, v95
	v_add_f32_e32 v94, 1.0, v94
	v_add_f32_e32 v95, 1.0, v95
	v_rcp_f32_e32 v94, v94
	v_rcp_f32_e32 v95, v95
	s_nop 0
	v_pk_mul_f32 v[82:83], v[82:83], v[94:95]
	s_nop 0
	v_pk_mul_f32 v[88:89], v[88:89], v[82:83]
	v_pk_mul_f32 v[82:83], v[92:93], v[150:151] op_sel_hi:[1,0]
	s_nop 0
	v_mul_f32_e32 v92, 0xbfb8aa3b, v82
	v_mul_f32_e32 v93, 0xbfb8aa3b, v83
	v_exp_f32_e32 v92, v92
	v_exp_f32_e32 v93, v93
	v_add_f32_e32 v92, 1.0, v92
	v_add_f32_e32 v93, 1.0, v93
	v_rcp_f32_e32 v92, v92
	v_rcp_f32_e32 v93, v93
	s_nop 0
	v_pk_mul_f32 v[82:83], v[82:83], v[92:93]
	s_nop 0
	v_pk_mul_f32 v[92:93], v[84:85], v[82:83]
	v_cvt_pk_bf16_f32 v82, v86, v87
	v_or_b32_e32 v86, 32, v153
	v_cvt_pk_bf16_f32 v83, v88, v89
	v_mul_lo_u32 v88, s13, v86
	v_mad_u64_u32 v[86:87], s[4:5], s12, v86, 0
	v_add3_u32 v87, v87, v116, v88
	v_lshl_add_u64 v[86:87], v[86:87], 1, s[62:63]
	v_cvt_pk_bf16_f32 v84, v90, v91
	v_cvt_pk_bf16_f32 v85, v92, v93
	v_lshl_add_u64 v[86:87], v[86:87], 0, v[114:115]
	global_store_dwordx4 v[86:87], v[82:85], off
	s_nop 1
	v_mul_f32_e32 v82, 0xbfb8aa3b, v78
	v_mul_f32_e32 v83, 0xbfb8aa3b, v79
	v_exp_f32_e32 v82, v82
	v_exp_f32_e32 v83, v83
	v_add_f32_e32 v82, 1.0, v82
	v_add_f32_e32 v83, 1.0, v83
	v_rcp_f32_e32 v82, v82
	v_rcp_f32_e32 v83, v83
	s_nop 0
	v_pk_mul_f32 v[78:79], v[78:79], v[82:83]
	s_nop 0
	v_pk_mul_f32 v[70:71], v[70:71], v[78:79]
	v_mul_f32_e32 v78, 0xbfb8aa3b, v74
	v_mul_f32_e32 v79, 0xbfb8aa3b, v75
	v_exp_f32_e32 v78, v78
	v_exp_f32_e32 v79, v79
	v_add_f32_e32 v78, 1.0, v78
	v_add_f32_e32 v79, 1.0, v79
	v_rcp_f32_e32 v78, v78
	v_rcp_f32_e32 v79, v79
	s_nop 0
	v_pk_mul_f32 v[74:75], v[74:75], v[78:79]
	s_nop 0
	v_pk_mul_f32 v[74:75], v[66:67], v[74:75]
	v_pk_mul_f32 v[66:67], v[80:81], v[148:149] op_sel_hi:[1,0]
	s_nop 0
	v_mul_f32_e32 v78, 0xbfb8aa3b, v66
	v_mul_f32_e32 v79, 0xbfb8aa3b, v67
	v_exp_f32_e32 v78, v78
	v_exp_f32_e32 v79, v79
	v_add_f32_e32 v78, 1.0, v78
	v_add_f32_e32 v79, 1.0, v79
	v_rcp_f32_e32 v78, v78
	v_rcp_f32_e32 v79, v79
	s_nop 0
	v_pk_mul_f32 v[66:67], v[66:67], v[78:79]
	s_nop 0
	v_pk_mul_f32 v[72:73], v[72:73], v[66:67]
	v_pk_mul_f32 v[66:67], v[76:77], v[148:149] op_sel_hi:[1,0]
	s_nop 0
	v_mul_f32_e32 v76, 0xbfb8aa3b, v66
	v_mul_f32_e32 v77, 0xbfb8aa3b, v67
	v_exp_f32_e32 v76, v76
	v_exp_f32_e32 v77, v77
	v_add_f32_e32 v76, 1.0, v76
	v_add_f32_e32 v77, 1.0, v77
	v_rcp_f32_e32 v76, v76
	v_rcp_f32_e32 v77, v77
	s_nop 0
	v_pk_mul_f32 v[66:67], v[66:67], v[76:77]
	s_nop 0
	v_pk_mul_f32 v[76:77], v[68:69], v[66:67]
	v_cvt_pk_bf16_f32 v66, v70, v71
	v_or_b32_e32 v70, 48, v153
	v_cvt_pk_bf16_f32 v67, v72, v73
	v_mul_lo_u32 v72, s13, v70
	v_mad_u64_u32 v[70:71], s[4:5], s12, v70, 0
	v_add3_u32 v71, v71, v116, v72
	v_lshl_add_u64 v[70:71], v[70:71], 1, s[62:63]
	v_cvt_pk_bf16_f32 v68, v74, v75
	v_cvt_pk_bf16_f32 v69, v76, v77
	v_lshl_add_u64 v[70:71], v[70:71], 0, v[114:115]
	global_store_dwordx4 v[70:71], v[66:69], off
	s_nop 1
	v_mul_f32_e32 v66, 0xbfb8aa3b, v62
	v_mul_f32_e32 v67, 0xbfb8aa3b, v63
	v_exp_f32_e32 v66, v66
	v_exp_f32_e32 v67, v67
	v_add_u32_e32 v68, 0x80, v153
	v_add_f32_e32 v66, 1.0, v66
	v_add_f32_e32 v67, 1.0, v67
	v_rcp_f32_e32 v66, v66
; __device__ __forceinline__ float silu_f(float x) { return x * __builtin_amdgcn_rcpf(1.f + __builtin_amdgcn_exp2f(-LOG2E * x)); }
; __device__ __forceinline__ u32x4 pk8(const f32x4 a, const f32x4 b) { u32x4 w; w.x = pk2(a[0], a[1]); w.y = pk2(a[2], a[3]); w.z = pk2(b[0], b[1]); w.w = pk2(b[2], b[3]); return w; }
; __device__ __forceinline__ float pre_get(const Pre& p, int ai, int m, int fr) { return __shfl(p.v[ai], m * 16 + fr); }
; __device__ __forceinline__ float rstd_pre(const float* ss, float v) { return ss ? rsqrtf(v * (1.0f / 2048.0f) + 1e-6f) : 1.0f; }
;     __device__ __forceinline__ void operator()(const Acc& acc, const Unit& u, int wr, int wc, int fr, int fq, const Pre& pre) const {
;     ...
; #pragma unroll
;         for (int ai = 0; ai < 2; ++ai)
; #pragma unroll
;             for (int m = 0; m < 4; ++m) rsq[ai][m] = rstd_pre(ss, pre_get(pre, ai, m, fr));
; #pragma unroll
;         for (int ai = 0; ai < 2; ++ai)
; #pragma unroll
;             for (int m = 0; m < 4; ++m) {
;                 f32x4 v0, v1; const float rs = rsq[ai][m];
; #pragma unroll
;                 for (int e = 0; e < 4; ++e) { v0[e] = silu_f(acc[ai][0][m][0][e] * rs) * (acc[ai][1][m][0][e] * rs); v1[e] = silu_f(acc[ai][0][m][1][e] * rs) * (acc[ai][1][m][1][e] * rs); }
;                 *(u32x4*)(O + (size_t)(row0 + ai * 128 + m * 16) * ldc + col0) = pk8(v0, v1);
;             }
	v_rcp_f32_e32 v67, v67
	s_nop 0
	v_pk_mul_f32 v[62:63], v[62:63], v[66:67]
	s_nop 0
	v_pk_mul_f32 v[54:55], v[54:55], v[62:63]
	v_mul_f32_e32 v62, 0xbfb8aa3b, v58
	v_mul_f32_e32 v63, 0xbfb8aa3b, v59
	v_exp_f32_e32 v62, v62
	v_exp_f32_e32 v63, v63
	v_add_f32_e32 v62, 1.0, v62
	v_add_f32_e32 v63, 1.0, v63
	v_rcp_f32_e32 v62, v62
	v_rcp_f32_e32 v63, v63
	s_nop 0
	v_pk_mul_f32 v[58:59], v[58:59], v[62:63]
	s_nop 0
	v_pk_mul_f32 v[58:59], v[50:51], v[58:59]
	v_pk_mul_f32 v[50:51], v[64:65], v[146:147] op_sel_hi:[1,0]
	s_nop 0
	v_mul_f32_e32 v62, 0xbfb8aa3b, v50
	v_mul_f32_e32 v63, 0xbfb8aa3b, v51
	v_exp_f32_e32 v62, v62
	v_exp_f32_e32 v63, v63
	v_add_f32_e32 v62, 1.0, v62
	v_add_f32_e32 v63, 1.0, v63
	v_rcp_f32_e32 v62, v62
	v_rcp_f32_e32 v63, v63
	s_nop 0
	v_pk_mul_f32 v[50:51], v[50:51], v[62:63]
	s_nop 0
	v_pk_mul_f32 v[56:57], v[56:57], v[50:51]
	v_pk_mul_f32 v[50:51], v[60:61], v[146:147] op_sel_hi:[1,0]
	s_nop 0
	v_mul_f32_e32 v60, 0xbfb8aa3b, v50
	v_mul_f32_e32 v61, 0xbfb8aa3b, v51
	v_exp_f32_e32 v60, v60
	v_exp_f32_e32 v61, v61
	v_add_f32_e32 v60, 1.0, v60
	v_add_f32_e32 v61, 1.0, v61
	v_rcp_f32_e32 v60, v60
	v_rcp_f32_e32 v61, v61
	s_nop 0
	v_pk_mul_f32 v[50:51], v[50:51], v[60:61]
	s_nop 0
	v_pk_mul_f32 v[60:61], v[52:53], v[50:51]
	v_cvt_pk_bf16_f32 v50, v54, v55
	v_ashrrev_i32_e32 v54, 31, v68
	v_cvt_pk_bf16_f32 v51, v56, v57
	v_mul_lo_u32 v56, s12, v54
	v_mul_lo_u32 v57, s13, v68
	v_mad_u64_u32 v[54:55], s[4:5], s12, v68, 0
	v_add3_u32 v55, v55, v56, v57
	v_lshl_add_u64 v[54:55], v[54:55], 1, s[62:63]
	v_cvt_pk_bf16_f32 v52, v58, v59
	v_cvt_pk_bf16_f32 v53, v60, v61
	v_lshl_add_u64 v[54:55], v[54:55], 0, v[114:115]
	global_store_dwordx4 v[54:55], v[50:53], off
	s_nop 1
	v_mul_f32_e32 v50, 0xbfb8aa3b, v46
	v_mul_f32_e32 v51, 0xbfb8aa3b, v47
	v_exp_f32_e32 v50, v50
	v_exp_f32_e32 v51, v51
	v_add_f32_e32 v50, 1.0, v50
	v_add_f32_e32 v51, 1.0, v51
	v_rcp_f32_e32 v50, v50
	v_rcp_f32_e32 v51, v51
	s_nop 0
	v_pk_mul_f32 v[46:47], v[46:47], v[50:51]
	s_nop 0
	v_pk_mul_f32 v[38:39], v[38:39], v[46:47]
	v_mul_f32_e32 v46, 0xbfb8aa3b, v42
	v_mul_f32_e32 v47, 0xbfb8aa3b, v43
	v_exp_f32_e32 v46, v46
	v_exp_f32_e32 v47, v47
	v_add_f32_e32 v46, 1.0, v46
	v_add_f32_e32 v47, 1.0, v47
	v_rcp_f32_e32 v46, v46
	v_rcp_f32_e32 v47, v47
	s_nop 0
	v_pk_mul_f32 v[42:43], v[42:43], v[46:47]
	s_nop 0
	v_pk_mul_f32 v[42:43], v[34:35], v[42:43]
	v_pk_mul_f32 v[34:35], v[48:49], v[144:145] op_sel_hi:[1,0]
	s_nop 0
	v_mul_f32_e32 v46, 0xbfb8aa3b, v34
	v_mul_f32_e32 v47, 0xbfb8aa3b, v35
	v_exp_f32_e32 v46, v46
	v_exp_f32_e32 v47, v47
	v_add_f32_e32 v46, 1.0, v46
	v_add_f32_e32 v47, 1.0, v47
	v_rcp_f32_e32 v46, v46
	v_rcp_f32_e32 v47, v47
	s_nop 0
	v_pk_mul_f32 v[34:35], v[34:35], v[46:47]
	s_nop 0
	v_pk_mul_f32 v[40:41], v[40:41], v[34:35]
	v_pk_mul_f32 v[34:35], v[44:45], v[144:145] op_sel_hi:[1,0]
	s_nop 0
	v_mul_f32_e32 v44, 0xbfb8aa3b, v34
	v_mul_f32_e32 v45, 0xbfb8aa3b, v35
	v_exp_f32_e32 v44, v44
	v_exp_f32_e32 v45, v45
	v_add_f32_e32 v44, 1.0, v44
	v_add_f32_e32 v45, 1.0, v45
	v_rcp_f32_e32 v44, v44
	v_rcp_f32_e32 v45, v45
	s_nop 0
	v_pk_mul_f32 v[34:35], v[34:35], v[44:45]
	s_nop 0
	v_pk_mul_f32 v[44:45], v[36:37], v[34:35]
	v_cvt_pk_bf16_f32 v34, v38, v39
	v_add_u32_e32 v38, 0x90, v153
	v_ashrrev_i32_e32 v39, 31, v38
	v_cvt_pk_bf16_f32 v35, v40, v41
	v_mul_lo_u32 v40, s12, v39
	v_mul_lo_u32 v41, s13, v38
	v_mad_u64_u32 v[38:39], s[4:5], s12, v38, 0
	v_add3_u32 v39, v39, v40, v41
	v_lshl_add_u64 v[38:39], v[38:39], 1, s[62:63]
	v_cvt_pk_bf16_f32 v36, v42, v43
	v_cvt_pk_bf16_f32 v37, v44, v45
	v_lshl_add_u64 v[38:39], v[38:39], 0, v[114:115]
	global_store_dwordx4 v[38:39], v[34:37], off
	s_nop 1
	v_mul_f32_e32 v34, 0xbfb8aa3b, v30
	v_mul_f32_e32 v35, 0xbfb8aa3b, v31
	v_exp_f32_e32 v34, v34
	v_exp_f32_e32 v35, v35
; __device__ __forceinline__ float silu_f(float x) { return x * __builtin_amdgcn_rcpf(1.f + __builtin_amdgcn_exp2f(-LOG2E * x)); }
; __device__ __forceinline__ u32x4 pk8(const f32x4 a, const f32x4 b) { u32x4 w; w.x = pk2(a[0], a[1]); w.y = pk2(a[2], a[3]); w.z = pk2(b[0], b[1]); w.w = pk2(b[2], b[3]); return w; }
; __device__ __forceinline__ float pre_get(const Pre& p, int ai, int m, int fr) { return __shfl(p.v[ai], m * 16 + fr); }
; __device__ __forceinline__ float rstd_pre(const float* ss, float v) { return ss ? rsqrtf(v * (1.0f / 2048.0f) + 1e-6f) : 1.0f; }
;     __device__ __forceinline__ void operator()(const Acc& acc, const Unit& u, int wr, int wc, int fr, int fq, const Pre& pre) const {
;     ...
; #pragma unroll
;         for (int ai = 0; ai < 2; ++ai)
; #pragma unroll
;             for (int m = 0; m < 4; ++m) rsq[ai][m] = rstd_pre(ss, pre_get(pre, ai, m, fr));
; #pragma unroll
;         for (int ai = 0; ai < 2; ++ai)
; #pragma unroll
;             for (int m = 0; m < 4; ++m) {
;                 f32x4 v0, v1; const float rs = rsq[ai][m];
; #pragma unroll
;                 for (int e = 0; e < 4; ++e) { v0[e] = silu_f(acc[ai][0][m][0][e] * rs) * (acc[ai][1][m][0][e] * rs); v1[e] = silu_f(acc[ai][0][m][1][e] * rs) * (acc[ai][1][m][1][e] * rs); }
;                 *(u32x4*)(O + (size_t)(row0 + ai * 128 + m * 16) * ldc + col0) = pk8(v0, v1);
;             }
	v_add_f32_e32 v34, 1.0, v34
	v_add_f32_e32 v35, 1.0, v35
	v_rcp_f32_e32 v34, v34
	v_rcp_f32_e32 v35, v35
	s_nop 0
	v_pk_mul_f32 v[30:31], v[30:31], v[34:35]
	s_nop 0
	v_pk_mul_f32 v[22:23], v[22:23], v[30:31]
	v_mul_f32_e32 v30, 0xbfb8aa3b, v26
	v_mul_f32_e32 v31, 0xbfb8aa3b, v27
	v_exp_f32_e32 v30, v30
	v_exp_f32_e32 v31, v31
	v_add_f32_e32 v30, 1.0, v30
	v_add_f32_e32 v31, 1.0, v31
	v_rcp_f32_e32 v30, v30
	v_rcp_f32_e32 v31, v31
	s_nop 0
	v_pk_mul_f32 v[26:27], v[26:27], v[30:31]
	s_nop 0
	v_pk_mul_f32 v[26:27], v[18:19], v[26:27]
	v_pk_mul_f32 v[18:19], v[32:33], v[142:143] op_sel_hi:[1,0]
	s_nop 0
	v_mul_f32_e32 v30, 0xbfb8aa3b, v18
	v_mul_f32_e32 v31, 0xbfb8aa3b, v19
	v_exp_f32_e32 v30, v30
	v_exp_f32_e32 v31, v31
	v_add_f32_e32 v30, 1.0, v30
	v_add_f32_e32 v31, 1.0, v31
	v_rcp_f32_e32 v30, v30
	v_rcp_f32_e32 v31, v31
	s_nop 0
	v_pk_mul_f32 v[18:19], v[18:19], v[30:31]
	s_nop 0
	v_pk_mul_f32 v[24:25], v[24:25], v[18:19]
	v_pk_mul_f32 v[18:19], v[28:29], v[142:143] op_sel_hi:[1,0]
	s_nop 0
	v_mul_f32_e32 v28, 0xbfb8aa3b, v18
	v_mul_f32_e32 v29, 0xbfb8aa3b, v19
	v_exp_f32_e32 v28, v28
	v_exp_f32_e32 v29, v29
	v_add_f32_e32 v28, 1.0, v28
	v_add_f32_e32 v29, 1.0, v29
	v_rcp_f32_e32 v28, v28
	v_rcp_f32_e32 v29, v29
	s_nop 0
	v_pk_mul_f32 v[18:19], v[18:19], v[28:29]
	s_nop 0
	v_pk_mul_f32 v[28:29], v[20:21], v[18:19]
	v_cvt_pk_bf16_f32 v18, v22, v23
	v_add_u32_e32 v22, 0xa0, v153
	v_ashrrev_i32_e32 v23, 31, v22
	v_cvt_pk_bf16_f32 v19, v24, v25
	v_mul_lo_u32 v24, s12, v23
	v_mul_lo_u32 v25, s13, v22
	v_mad_u64_u32 v[22:23], s[4:5], s12, v22, 0
	v_add3_u32 v23, v23, v24, v25
	v_lshl_add_u64 v[22:23], v[22:23], 1, s[62:63]
	v_cvt_pk_bf16_f32 v20, v26, v27
	v_cvt_pk_bf16_f32 v21, v28, v29
	v_lshl_add_u64 v[22:23], v[22:23], 0, v[114:115]
	global_store_dwordx4 v[22:23], v[18:21], off
	s_nop 1
	v_mul_f32_e32 v18, 0xbfb8aa3b, v14
	v_mul_f32_e32 v19, 0xbfb8aa3b, v15
	v_exp_f32_e32 v18, v18
	v_exp_f32_e32 v19, v19
	v_add_f32_e32 v18, 1.0, v18
	v_add_f32_e32 v19, 1.0, v19
	v_rcp_f32_e32 v18, v18
	v_rcp_f32_e32 v19, v19
	s_nop 0
	v_pk_mul_f32 v[14:15], v[14:15], v[18:19]
	s_nop 0
	v_pk_mul_f32 v[6:7], v[6:7], v[14:15]
	v_mul_f32_e32 v14, 0xbfb8aa3b, v10
	v_mul_f32_e32 v15, 0xbfb8aa3b, v11
	v_exp_f32_e32 v14, v14
	v_exp_f32_e32 v15, v15
	v_add_f32_e32 v14, 1.0, v14
	v_add_f32_e32 v15, 1.0, v15
	v_rcp_f32_e32 v14, v14
	v_rcp_f32_e32 v15, v15
	s_nop 0
	v_pk_mul_f32 v[10:11], v[10:11], v[14:15]
	s_nop 0
	v_pk_mul_f32 v[10:11], v[2:3], v[10:11]
	v_pk_mul_f32 v[2:3], v[16:17], v[140:141] op_sel_hi:[1,0]
	s_nop 0
	v_mul_f32_e32 v14, 0xbfb8aa3b, v2
	v_mul_f32_e32 v15, 0xbfb8aa3b, v3
	v_exp_f32_e32 v14, v14
	v_exp_f32_e32 v15, v15
	v_add_f32_e32 v14, 1.0, v14
	v_add_f32_e32 v15, 1.0, v15
	v_rcp_f32_e32 v14, v14
	v_rcp_f32_e32 v15, v15
	s_nop 0
	v_pk_mul_f32 v[2:3], v[2:3], v[14:15]
	s_nop 0
	v_pk_mul_f32 v[8:9], v[8:9], v[2:3]
	v_pk_mul_f32 v[2:3], v[12:13], v[140:141] op_sel_hi:[1,0]
	s_nop 0
	v_mul_f32_e32 v12, 0xbfb8aa3b, v2
	v_mul_f32_e32 v13, 0xbfb8aa3b, v3
	v_exp_f32_e32 v12, v12
	v_exp_f32_e32 v13, v13
	v_add_f32_e32 v12, 1.0, v12
	v_add_f32_e32 v13, 1.0, v13
	v_rcp_f32_e32 v12, v12
	v_rcp_f32_e32 v13, v13
	s_nop 0
	v_pk_mul_f32 v[2:3], v[2:3], v[12:13]
	s_nop 0
	v_pk_mul_f32 v[12:13], v[4:5], v[2:3]
	v_cvt_pk_bf16_f32 v2, v6, v7
	v_add_u32_e32 v6, 0xb0, v153
	v_ashrrev_i32_e32 v7, 31, v6
	v_cvt_pk_bf16_f32 v3, v8, v9
	v_mul_lo_u32 v8, s12, v7
	v_mul_lo_u32 v9, s13, v6
	v_mad_u64_u32 v[6:7], s[4:5], s12, v6, 0
	v_add3_u32 v7, v7, v8, v9
	v_lshl_add_u64 v[6:7], v[6:7], 1, s[62:63]
	v_cvt_pk_bf16_f32 v4, v10, v11
	v_cvt_pk_bf16_f32 v5, v12, v13
	v_lshl_add_u64 v[6:7], v[6:7], 0, v[114:115]
	s_mov_b64 s[4:5], s[64:65]
	global_store_dwordx4 v[6:7], v[2:5], off
	s_cbranch_vccz .LBB0_813
	s_branch .LBB0_828

; #define PG8_WAIT_V(n) asm volatile("s_waitcnt vmcnt(" #n ")" ::: "memory")
; #define PG8_BAR __builtin_amdgcn_s_barrier()
; template <class Epi>
; __device__ __forceinline__ void gemm_phase(LAS unsigned char* lds, const Gemm g, const Sched& S, const Epi& E) {
;     ...
;     PG8_WAIT_V(0);
;     if (wr == 0) PG8_BAR;
;     PG8_BAR;
.LBB0_828:
	s_waitcnt vmcnt(0)
	s_cmpk_gt_u32 s2, 0xff
	s_cbranch_scc1 .LBB0_830
.LBB0_830:
	v_readlane_b32 s58, v253, 45
	v_readlane_b32 s64, v253, 47
	s_mov_b32 s72, s89
	s_barrier
	v_readlane_b32 s59, v253, 46
